# pipelined weight-conversion loops (4 tiles in flight), conversion moved to idle WGs of scan phase, in-proj tail/dt units spread over all WGs
# baseline (speedup 1.0000x reference)
; #define LAS __attribute__((address_space(3)))
; __device__ __forceinline__ void run_phase(LAS unsigned char* lds, KP& P_, int ph) {
;     unsigned char* ob = (unsigned char*)p.out; unsigned char* ws = p.ws;
;     if (ph == 0) { phase_init(P_); weights_units(lds, P_, -1, 0, (int)blockIdx.x, (int)gridDim.x); for (int lt = 0; lt < DEPTH; ++lt) tables_units(lds, P_, lt, 49 + 7 * lt); return; }
;     if (ph == NPHASE - 1) { phase_final(P_); return; }
;     int l = (ph - 1) / 7, k = (ph - 1) % 7; asm volatile("" : "+s"(l), "+s"(k));
;     bf16_t* xb = (bf16_t*)(ws + WS_PRE);
;     float* statA = (float*)(ws + WS_STAT0); float* statB = (float*)(ws + WS_STAT1);
;     const bool tail_first = ((blockIdx.x >> 3) & 1) != 0;
;     if (k == 0) { EpiInProj E{statB, (const float*)(ws + WS_C1IN), (const float*)(ws + WS_C2IN), (bf16_t*)(ws + WS_PROJ), (float*)(ws + WS_DT), p.in[7] + l * 6, nullptr, l > 0 ? 1 : 0};
;         const int hrank = (((int)blockIdx.x >> 4) << 3) | ((int)blockIdx.x & 7), hsize = (int)gridDim.x >> 1;
;         zero_tail_stats(statA);
;         if (tail_first) weights_units(lds, P_, l, -1, hrank, hsize);
;         gemm_phase(lds, xb, (const bf16_t*)(ob + OUT_WIN), 1024, 64, 12, E);
;         if (!tail_first) {
;             gemm_tail(lds, xb, (const bf16_t*)(ob + OUT_WIN), 1024, NPROJ, E, hrank, hsize);
;             dt_units(lds, xb, (const bf16_t*)(ob + OUT_WIN), statB, (const float*)(ws + WS_C1IN), (const float*)(ws + WS_C2IN), (float*)(ws + WS_DT), l > 0 ? 1 : 0, (bf16_t*)(ws + WS_PROJ), hrank, hsize, 2 * hsize); }
;         else if (2 * hsize + hrank < NCHT)
;             dt_units(lds, xb, (const bf16_t*)(ob + OUT_WIN), statB, (const float*)(ws + WS_C1IN), (const float*)(ws + WS_C2IN), (float*)(ws + WS_DT), l > 0 ? 1 : 0, (bf16_t*)(ws + WS_PROJ), 2 * hsize + hrank, NCHT, NCHT);
.LBB0_20:
	s_mov_b32 s6, s2
	s_lshl_b32 s2, s2, 3
	v_writelane_b32 v253, s2, 6
	s_mov_b32 s91, 0
	v_readlane_b32 s2, v253, 0
	v_readlane_b32 s3, v253, 1
	s_add_u32 s2, s2, 0xf8
	s_addc_u32 s3, s3, 0
	v_writelane_b32 v253, s2, 7
	s_mov_b32 s7, s91
	v_and_b32_e32 v198, 0x3ff, v0
	v_writelane_b32 v253, s3, 8
	s_lshl_b64 s[2:3], s[6:7], 9
	v_writelane_b32 v253, s2, 9
	s_cmp_lt_i32 s6, 49
	v_mov_b32_e32 v1, 0
	v_writelane_b32 v253, s3, 10
	s_cselect_b64 s[2:3], -1, 0
	v_writelane_b32 v253, s2, 11
	v_mbcnt_lo_u32_b32 v0, -1, 0
	v_mbcnt_hi_u32_b32 v204, -1, v0
	v_writelane_b32 v253, s3, 12
	s_sub_i32 s2, s6, 49
	v_writelane_b32 v253, s2, 13
	s_and_b32 s2, s6, 8
	s_cmp_eq_u32 s2, 0
	s_cselect_b64 s[4:5], -1, 0
	v_writelane_b32 v253, s4, 14
	s_cmp_lg_u32 s2, 0
	s_cselect_b64 s[2:3], -1, 0
	v_writelane_b32 v253, s5, 15
	v_writelane_b32 v253, s2, 16
	s_cmp_eq_u32 s6, 0
	v_and_b32_e32 v205, 64, v204
	v_writelane_b32 v253, s3, 17
	s_cselect_b64 s[2:3], -1, 0
	v_writelane_b32 v253, s2, 18
	s_cmpk_lt_i32 s6, 0x100
	v_mov_b32_e32 v200, 0x358637bd
	v_writelane_b32 v253, s3, 19
	s_cselect_b64 s[2:3], -1, 0
	v_writelane_b32 v253, s2, 20
	s_lshl_b32 s5, s6, 4
	v_mov_b32_e32 v201, 0x3c0881c4
	v_writelane_b32 v253, s3, 21
	s_and_b32 s2, s6, 3
	s_mul_i32 s3, s2, 0x1040
	v_writelane_b32 v253, s3, 22
	s_addk_i32 s3, 0x1030
	v_writelane_b32 v253, s3, 23
	s_and_b32 s3, s5, 0xffffffc0
	s_cmpk_lt_i32 s6, 0x400
	v_writelane_b32 v253, s3, 24
	s_cselect_b64 s[8:9], -1, 0
	s_ashr_i32 s3, s6, 31
	s_lshr_b32 s3, s3, 26
	s_add_i32 s3, s6, s3
	v_writelane_b32 v253, s8, 25
	s_ashr_i32 s12, s3, 6
	s_andn2_b32 s3, s3, 63
	v_writelane_b32 v253, s9, 26
	s_sub_i32 s4, s6, s3
	s_lshr_b32 s3, s4, 4
	v_writelane_b32 v253, s4, 27
	s_lshl_b32 s4, s4, 8
	s_mulk_i32 s3, 0x1040
	s_and_b32 s4, s4, 0xf00
	s_add_i32 s4, s4, s3
	s_or_b32 s14, s4, 48
	s_ashr_i32 s15, s14, 31
	s_lshl_b64 s[8:9], s[14:15], 11
	v_writelane_b32 v253, s8, 28
	s_ashr_i32 s13, s12, 31
	s_and_b32 s3, s5, 0xffffff40
	v_writelane_b32 v253, s9, 29
	s_lshl_b64 s[8:9], s[12:13], 19
	v_writelane_b32 v253, s8, 30
	s_lshl_b32 s4, s6, 2
	s_lshl_b32 s2, s2, 4
	v_writelane_b32 v253, s9, 31
	v_writelane_b32 v253, s5, 32
	v_writelane_b32 v253, s3, 33
	s_and_b32 s3, s4, -16
	v_writelane_b32 v253, s3, 34
	v_writelane_b32 v253, s2, 35
	s_ashr_i32 s2, s6, 4
	s_ashr_i32 s3, s2, 31
	s_lshl_b64 s[2:3], s[2:3], 3
	v_writelane_b32 v253, s2, 36
	v_mov_b32_e32 v202, 0xbab64f3b
	v_mov_b32_e32 v177, 2.0
	v_writelane_b32 v253, s3, 37
	s_and_b32 s2, s4, 0xffffffd0
	v_writelane_b32 v253, s2, 38
	s_lshl_b32 s2, s6, 9
	v_writelane_b32 v253, s2, 39
	s_add_i32 s2, s6, 0xffffff98
	v_writelane_b32 v253, s2, 40
	s_ashr_i32 s2, s6, 1
	s_and_b32 s3, s2, -8
	s_and_b32 s4, s6, 7
	s_or_b32 s3, s3, s4
	s_mov_b32 s3, s6
	s_cmpk_lt_i32 s6, 0x300
	s_cselect_b64 s[8:9], -1, 0
	v_writelane_b32 v253, s8, 41
	s_cmpk_lt_i32 s3, 0xc0
	v_mov_b32_e32 v203, 1
	v_writelane_b32 v253, s9, 42
	s_cselect_b64 s[8:9], -1, 0
	v_writelane_b32 v253, s8, 43
	v_add_u32_e32 v206, 64, v205
	v_xor_b32_e32 v207, 1, v204
	v_writelane_b32 v253, s9, 44
	v_writelane_b32 v253, s3, 45
	s_lshl_b32 s3, s3, 4
	s_andn2_b32 s3, s3, 63
	v_writelane_b32 v253, s3, 46
	s_mov_b32 s8, s14
	v_writelane_b32 v253, s8, 47
	v_xor_b32_e32 v208, 2, v204
	v_xor_b32_e32 v252, 8, v204
	v_writelane_b32 v253, s9, 48
	s_lshl_b64 s[8:9], s[14:15], 13
	v_writelane_b32 v253, s8, 49
	v_not_b32_e32 v212, 47
	v_mov_b32_e32 v213, 0x7f800000
	v_writelane_b32 v253, s9, 50
	s_mov_b32 s8, s12
	v_writelane_b32 v253, s8, 51
	v_mov_b32_e32 v178, 0x3f317218
	v_bfrev_b32_e32 v214, 0.5
	v_writelane_b32 v253, s9, 52
	s_lshl_b64 s[8:9], s[12:13], 21
	v_writelane_b32 v253, s8, 53
	v_mov_b32_e32 v215, 0x1800
	v_mov_b32_e32 v199, 0x3200
	v_writelane_b32 v253, s9, 54
	v_mov_b32_e32 v209, 0x1200
	v_readlane_b32 s12, v253, 2
	v_readlane_b32 s13, v253, 3
	s_add_u32 s8, s12, 0xeef0a00
	s_addc_u32 s9, s13, 0
	v_readlane_b32 s14, v253, 4
	v_readlane_b32 s15, v253, 5
	v_writelane_b32 v253, s8, 55
	v_mov_b32_e32 v4, v1
	v_mov_b32_e32 v5, v1
	v_writelane_b32 v253, s9, 56
	s_add_u32 s8, s12, 0xeef0c00
	s_addc_u32 s9, s13, 0
	v_writelane_b32 v253, s8, 57
	v_mov_b32_e32 v6, v1
	v_mov_b32_e32 v7, v1
	v_writelane_b32 v253, s9, 58
	s_add_u32 s8, s12, 0xeef0d00
	s_addc_u32 s9, s13, 0
	v_writelane_b32 v253, s8, 59
	v_mov_b32_e32 v218, 0xf149f2ca
	v_not_b32_e32 v219, 63
	v_writelane_b32 v253, s9, 60
	s_add_u32 s8, s12, 0xeef0e00
	s_addc_u32 s9, s13, 0
	v_writelane_b32 v253, s8, 61
	v_not_b32_e32 v220, 31
	v_mov_b32_e32 v221, 0x7fc00000
	v_writelane_b32 v253, s9, 62
	s_add_u32 s8, s12, 0xeef0f00
	s_addc_u32 s9, s13, 0
	v_writelane_b32 v253, s8, 63
	s_mov_b32 s33, 0x10000
	s_mov_b32 s16, 0x20000
	v_writelane_b32 v254, s9, 0
	s_add_u32 s8, s12, 0xeef1000
	s_addc_u32 s9, s13, 0
	v_writelane_b32 v254, s8, 1
	s_mov_b32 s92, 0xc0135761
	s_mov_b32 s17, 0x3fb8aa3b
	v_writelane_b32 v254, s9, 2
	s_add_u32 s8, s12, 0xeef1100
	s_addc_u32 s9, s13, 0
	v_writelane_b32 v254, s8, 3
	s_mov_b32 s93, 0xc2ce8ed0
	s_mov_b32 s5, 0x42b17218
	v_writelane_b32 v254, s9, 4
	s_add_u32 s8, s12, 0xeef1200
	s_addc_u32 s9, s13, 0
	v_writelane_b32 v254, s8, 5
	s_mov_b32 s83, 0x2aaaaaab
	s_mov_b32 s11, 0x30000
	v_writelane_b32 v254, s9, 6
	s_add_u32 s8, s12, 0xeef1300
	s_addc_u32 s9, s13, 0
; __device__ __forceinline__ unsigned xb_ld(unsigned* q)              { return __hip_atomic_load(q, __ATOMIC_RELAXED, __HIP_MEMORY_SCOPE_AGENT); }
; __device__ __forceinline__ void xcd_barrier_complete(unsigned* bar, unsigned x, unsigned& nloc, unsigned& nx) {
;     const unsigned G = gridDim.x * gridDim.y * gridDim.z;
;     unsigned sum, cnt, mine, sp = 0u;
;     for (;;) {
;         sum = 0u; cnt = 0u; mine = 0u;
; #pragma unroll
;         for (unsigned j = 0; j < 16; ++j) { const unsigned c = xb_ld(&bar[XB_XCNT(j)]); sum += c; cnt += (c > 0u) ? 1u : 0u; mine = (j == x) ? c : mine; }
;         if (sum == G) break;
;         __builtin_amdgcn_s_sleep(1);
;         if ((++sp & 255u) == 0u) { if (xb_ld(&bar[XB_TMO])) break; if (sp > XB_SPIN_CAP) { atomicAdd(&bar[XB_TMO], 1u); break; } }
;     }
;     nloc = mine > 0u ? mine : 1u; nx = cnt > 0u ? cnt : 1u;
; }
; __device__ __forceinline__ void run_phase(LAS unsigned char* lds, KP& P_, int ph) {
;     ...
;     const bool tail_first = ((blockIdx.x >> 3) & 1) != 0;
;     if (k == 0) { EpiInProj E{statB, (const float*)(ws + WS_C1IN), (const float*)(ws + WS_C2IN), (bf16_t*)(ws + WS_PROJ), (float*)(ws + WS_DT), p.in[7] + l * 6, nullptr, l > 0 ? 1 : 0};
;         const int hrank = (((int)blockIdx.x >> 4) << 3) | ((int)blockIdx.x & 7), hsize = (int)gridDim.x >> 1;
;         zero_tail_stats(statA);
;         if (tail_first) weights_units(lds, P_, l, -1, hrank, hsize);
;         gemm_phase(lds, xb, (const bf16_t*)(ob + OUT_WIN), 1024, 64, 12, E);
;         if (!tail_first) {
;             gemm_tail(lds, xb, (const bf16_t*)(ob + OUT_WIN), 1024, NPROJ, E, hrank, hsize);
;             dt_units(lds, xb, (const bf16_t*)(ob + OUT_WIN), statB, (const float*)(ws + WS_C1IN), (const float*)(ws + WS_C2IN), (float*)(ws + WS_DT), l > 0 ? 1 : 0, (bf16_t*)(ws + WS_PROJ), hrank, hsize, 2 * hsize); }
;         else if (2 * hsize + hrank < NCHT)
;             dt_units(lds, xb, (const bf16_t*)(ob + OUT_WIN), statB, (const float*)(ws + WS_C1IN), (const float*)(ws + WS_C2IN), (float*)(ws + WS_DT), l > 0 ? 1 : 0, (bf16_t*)(ws + WS_PROJ), 2 * hsize + hrank, NCHT, NCHT);
	v_writelane_b32 v254, s8, 7
	s_mov_b32 s27, 0xfc2757d1
	s_mov_b32 s82, 0xa2f9836e
	v_writelane_b32 v254, s9, 8
	s_add_u32 s8, s12, 0xeef1400
	s_addc_u32 s9, s13, 0
	v_writelane_b32 v254, s8, 9
	s_mov_b32 s28, 0x3fc90fda
	s_mov_b32 s29, 0xbfc90fda
	v_writelane_b32 v254, s9, 10
	s_add_u32 s8, s12, 0xeef1500
	s_addc_u32 s9, s13, 0
	v_writelane_b32 v254, s8, 11
	s_mov_b64 s[38:39], 0xef19000
	s_mov_b64 s[80:81], 0xef09000
	v_writelane_b32 v254, s9, 12
	s_add_u32 s8, s12, 0xeef1600
	s_addc_u32 s9, s13, 0
	v_writelane_b32 v254, s8, 13
	s_mov_b64 s[94:95], 0x80
	s_mov_b64 s[88:89], 0x100000
	v_writelane_b32 v254, s9, 14
	s_add_u32 s8, s12, 0xeef1700
	s_addc_u32 s9, s13, 0
	v_writelane_b32 v254, s8, 15
	s_nop 1
	v_writelane_b32 v254, s9, 16
	s_add_u32 s8, s12, 0xeef1800
	s_addc_u32 s9, s13, 0
	v_writelane_b32 v254, s8, 17
	s_nop 1
	v_writelane_b32 v254, s9, 18
	s_add_u32 s8, s12, 0xeef1900
	s_addc_u32 s9, s13, 0
	v_writelane_b32 v254, s8, 19
	s_nop 1
	v_writelane_b32 v254, s9, 20
	s_add_u32 s8, s12, 0xeef1a00
	s_addc_u32 s9, s13, 0
	v_writelane_b32 v254, s8, 21
	s_nop 1
	v_writelane_b32 v254, s9, 22
	s_add_u32 s8, s12, 0xeef1b00
	s_addc_u32 s9, s13, 0
	v_writelane_b32 v254, s8, 23
	s_cmp_eq_u32 s10, 15
	s_nop 0
	v_writelane_b32 v254, s9, 24
	s_cselect_b64 s[8:9], -1, 0
	v_writelane_b32 v254, s8, 25
	s_cmp_eq_u32 s10, 14
	s_nop 0
	v_writelane_b32 v254, s9, 26
	s_cselect_b64 s[8:9], -1, 0
	v_writelane_b32 v254, s8, 27
	s_cmp_eq_u32 s10, 13
	s_nop 0
	v_writelane_b32 v254, s9, 28
	s_cselect_b64 s[8:9], -1, 0
	v_writelane_b32 v254, s8, 29
	s_cmp_eq_u32 s10, 12
	s_nop 0
	v_writelane_b32 v254, s9, 30
	s_cselect_b64 s[8:9], -1, 0
	v_writelane_b32 v254, s8, 31
	s_cmp_eq_u32 s10, 11
	s_nop 0
	v_writelane_b32 v254, s9, 32
	s_cselect_b64 s[8:9], -1, 0
	v_writelane_b32 v254, s8, 33
	s_cmp_eq_u32 s10, 10
	s_nop 0
	v_writelane_b32 v254, s9, 34
	s_cselect_b64 s[8:9], -1, 0
	v_writelane_b32 v254, s8, 35
	s_cmp_eq_u32 s10, 9
	s_nop 0
	v_writelane_b32 v254, s9, 36
	s_cselect_b64 s[8:9], -1, 0
	v_writelane_b32 v254, s8, 37
	s_cmp_eq_u32 s10, 8
	s_nop 0
	v_writelane_b32 v254, s9, 38
	s_cselect_b64 s[8:9], -1, 0
	v_writelane_b32 v254, s8, 39
	s_cmp_eq_u32 s10, 7
	s_nop 0
	v_writelane_b32 v254, s9, 40
	s_cselect_b64 s[8:9], -1, 0
	v_writelane_b32 v254, s8, 41
	s_cmp_eq_u32 s10, 6
	s_nop 0
	v_writelane_b32 v254, s9, 42
	s_cselect_b64 s[8:9], -1, 0
	v_writelane_b32 v254, s8, 43
	s_cmp_eq_u32 s10, 5
	s_nop 0
	v_writelane_b32 v254, s9, 44
	s_cselect_b64 s[8:9], -1, 0
	v_writelane_b32 v254, s8, 45
	s_cmp_eq_u32 s10, 4
	s_nop 0
	v_writelane_b32 v254, s9, 46
	s_cselect_b64 s[8:9], -1, 0
	v_writelane_b32 v254, s8, 47
	s_cmp_eq_u32 s10, 3
	s_nop 0
	v_writelane_b32 v254, s9, 48
	s_cselect_b64 s[8:9], -1, 0
	v_writelane_b32 v254, s8, 49
	s_cmp_eq_u32 s10, 2
	s_nop 0
	v_writelane_b32 v254, s9, 50
	s_cselect_b64 s[8:9], -1, 0
	v_writelane_b32 v254, s8, 51
	s_cmp_eq_u32 s10, 1
	s_nop 0
	v_writelane_b32 v254, s9, 52
	s_cselect_b64 s[8:9], -1, 0
	v_writelane_b32 v254, s8, 53
	s_cmp_eq_u32 s10, 0
	s_nop 0
	v_writelane_b32 v254, s9, 54
	s_cselect_b64 s[8:9], -1, 0
	s_lshl_b32 s3, s10, 8
	s_add_u32 s0, s0, s3
	v_writelane_b32 v254, s8, 55
	s_addc_u32 s1, s1, 0
	s_movk_i32 s10, 0x90
	v_writelane_b32 v254, s9, 56
	s_add_u32 s8, s0, 0x1400
	s_addc_u32 s9, s1, 0
	v_writelane_b32 v254, s8, 57
	s_add_u32 s0, s0, 0x2400
	s_addc_u32 s1, s1, 0
	v_writelane_b32 v254, s9, 58
	v_writelane_b32 v254, s0, 59
	s_movk_i32 s9, 0x1800
	s_mov_b32 s8, 0x4e441529
	v_writelane_b32 v254, s1, 60
	s_add_u32 s0, s12, 0xeef3c00
	s_addc_u32 s1, s13, 0
	v_writelane_b32 v254, s0, 61
	s_nop 1
	v_writelane_b32 v254, s1, 62
	s_add_u32 s0, s12, 0xeef3d00
	s_addc_u32 s1, s13, 0
	v_writelane_b32 v254, s0, 63
	s_nop 1
	v_writelane_b32 v255, s1, 0
	s_lshr_b32 s0, s2, 3
	s_lshl_b32 s1, s0, 9
	s_lshl_b32 s2, s4, 6
	s_or_b32 s2, s1, s2
	s_lshl_b32 s0, s0, 7
	s_lshl_b32 s1, s4, 4
	s_or_b32 s0, s0, s1
	s_lshl_b32 s0, s6, 4
	v_writelane_b32 v255, s0, 1
	s_lshl_b32 s0, s6, 6
	v_writelane_b32 v255, s0, 2
	s_lshl_b32 s0, s6, 11
	v_writelane_b32 v255, s0, 3
	s_lshl_b32 s0, s6, 12
	v_writelane_b32 v255, s0, 4
	v_writelane_b32 v255, s2, 5
	s_add_i32 s0, s2, 0xffffe000
	v_writelane_b32 v255, s0, 6
	s_add_i32 s0, 0, 0x23fe0
	v_writelane_b32 v255, s0, 7
	s_add_i32 s0, 0, 0x23fe4
	v_writelane_b32 v255, s0, 8
	s_add_i32 s0, 0, 0x16b00
	v_writelane_b32 v255, s0, 9
	s_add_i32 s0, 0, 0x640
	v_writelane_b32 v255, s0, 10
	s_add_i32 s0, 0, 0x16900
	v_writelane_b32 v255, s0, 11
	s_add_i32 s0, 0, 0x4100
	v_writelane_b32 v255, s0, 12
	s_add_i32 s0, 0, 0xb500
	v_writelane_b32 v255, s0, 13
	s_add_i32 s0, 0, 0x6c00
	v_writelane_b32 v255, s0, 14
	s_add_i32 s0, 0, 0x4900
	v_writelane_b32 v255, s0, 15
	s_add_i32 s0, 0, 0x6d00
	v_writelane_b32 v255, s0, 16
	s_add_i32 s0, 0, 0x23ff0
	v_writelane_b32 v255, s0, 17
	s_add_i32 s0, 0, 0x23ff4
	v_writelane_b32 v255, s0, 18
	v_cmp_eq_u32_e64 s[2:3], 0, v198
	s_movk_i32 s1, 0x100
	s_mov_b32 s0, s6
	v_writelane_b32 v255, s2, 19
	s_mov_b32 s4, 0x3fd744fd
	s_nop 0
	v_writelane_b32 v255, s3, 20
	v_writelane_b32 v255, s0, 21
	s_lshl_b64 s[2:3], s[6:7], 11
	s_nop 0
	v_writelane_b32 v255, s1, 22
	v_writelane_b32 v255, s2, 23
	s_mov_b32 s0, 0x3a800000
	s_nop 0
	v_writelane_b32 v255, s3, 24
	s_mov_b64 s[2:3], 0xc0600
	s_branch .LBB0_24

; #define LAS __attribute__((address_space(3)))
; __device__ void weights_units(LAS unsigned char* lds, KP& P0, int lm0, int li0, int ufirst, int ustride) {
;     const int n_m = lm0 >= 0 ? 144 : 0, n_i = li0 >= 0 ? 49 : 0, NU = n_m + n_i;
;     for (int u = ufirst; u < NU; u += ustride) {
;         KPtr P_ = P0; int lm = __builtin_amdgcn_readfirstlane(lm0), li = __builtin_amdgcn_readfirstlane(li0); asm volatile("" : "+s"(P_.q), "+s"(lm), "+s"(li));
;         unsigned char* ob = (unsigned char*)p.out; unsigned char* ws = p.ws;
;         if (u < n_m) {
;             if (u < 64) { const float* w1 = p.in[24] + (size_t)lm * DM * DFF;
;                 conv_unit(lds, w1, DFF, u * 64, 64, 0, 1024, (bf16_t*)(ob + OUT_W1), u * 64, 1024, 0, p.in[22] + (size_t)lm * DM, p.in[23] + (size_t)lm * DM, (float*)(ws + WS_C1MLP), (float*)(ws + WS_C2MLP)); }
;             else if (u < 128) { const int j = (u - 64) & 15, kq = (u - 64) >> 4; const float* w2 = p.in[25] + (size_t)lm * DFF * DM;
;                 conv_unit(lds, w2, DM, j * 64, 64, kq * 1024, 1024, (bf16_t*)(ob + OUT_W2), j * 64, DFF, kq * 1024, nullptr, nullptr, nullptr, nullptr); }
;             else { const int j = u - 128; const float* w_out = p.in[21] + (size_t)lm * DM * DM;
;                 conv_unit(lds, w_out, DM, j * 64, 64, 0, 1024, (bf16_t*)(ob + OUT_WOUT), j * 64, 1024, 0, nullptr, nullptr, nullptr, nullptr); }
; __device__ __forceinline__ void run_phase(LAS unsigned char* lds, KP& P_, int ph) {
;     ...
;     else if (k == 2) { phase_mix_b(P_, l); weights_units(lds, P_, -1, l < DEPTH - 1 ? l + 1 : -1, ((int)blockIdx.x - 104 + (int)gridDim.x) % (int)gridDim.x, (int)gridDim.x);
.LBB0_596:
	v_readlane_b32 s53, v255, 21
	s_nop 1
	s_sub_i32 s53, s53, 153
	s_cmp_lt_i32 s53, 0
	s_cbranch_scc1 .Lk2_conv_done
	s_movk_i32 s13, 0x90
	s_movk_i32 s56, 103
	s_movk_i32 s52, 6592
	s_lshl_b32 s6, s53, 6
	s_add_i32 s18, s6, 0xffffe000
	s_branch .LBB0_805

; __device__ __forceinline__ void run_phase(LAS unsigned char* lds, KP& P_, int ph) {
;     ...
;     if (k == 0) { EpiInProj E{statB, (const float*)(ws + WS_C1IN), (const float*)(ws + WS_C2IN), (bf16_t*)(ws + WS_PROJ), (float*)(ws + WS_DT), p.in[7] + l * 6, nullptr, l > 0 ? 1 : 0};
;         const int hrank = (((int)blockIdx.x >> 4) << 3) | ((int)blockIdx.x & 7), hsize = (int)gridDim.x >> 1;
;         zero_tail_stats(statA);
;         if (tail_first) weights_units(lds, P_, l, -1, hrank, hsize);
;         gemm_phase(lds, xb, (const bf16_t*)(ob + OUT_WIN), 1024, 64, 12, E);
.LBB0_789:
	s_and_b64 vcc, exec, s[12:13]
	s_cbranch_vccz .LBB0_928
	v_readlane_b32 s6, v253, 7
	v_readlane_b32 s7, v253, 8
	s_load_dword s57, s[6:7], 0x0
	v_readlane_b32 s6, v253, 18
	v_readlane_b32 s7, v253, 19
	s_andn2_b64 vcc, exec, s[6:7]
	s_cbranch_vccz .LBB0_792
	s_and_b64 vcc, exec, s[40:41]
	s_waitcnt lgkmcnt(0)
	s_mov_b32 s56, s57
	s_branch .LBB0_832

; __device__ __forceinline__ void run_phase(LAS unsigned char* lds, KP& P_, int ph) {
;     ...
;     if (k == 0) { EpiInProj E{statB, (const float*)(ws + WS_C1IN), (const float*)(ws + WS_C2IN), (bf16_t*)(ws + WS_PROJ), (float*)(ws + WS_DT), p.in[7] + l * 6, nullptr, l > 0 ? 1 : 0};
;         const int hrank = (((int)blockIdx.x >> 4) << 3) | ((int)blockIdx.x & 7), hsize = (int)gridDim.x >> 1;
;         zero_tail_stats(statA);
;         if (tail_first) weights_units(lds, P_, l, -1, hrank, hsize);
;         gemm_phase(lds, xb, (const bf16_t*)(ob + OUT_WIN), 1024, 64, 12, E);
.LBB0_800:
	s_or_b64 exec, exec, s[6:7]
	s_and_b64 vcc, exec, s[40:41]
	s_waitcnt lgkmcnt(0)
	s_mov_b32 s56, s57
	s_branch .LBB0_832

; #define LAS __attribute__((address_space(3)))
; __device__ __forceinline__ bf16_t f2bf(float f) { return (bf16_t)(cvt_pk_bf16(f, 0.f) & 0xffffu); }
; __device__ __forceinline__ float bf2f(bf16_t b) { return __uint_as_float(((unsigned)b) << 16); }
; __device__ __forceinline__ int tidx() { int t = threadIdx.x; asm volatile("" : "+v"(t)); return t; }
; __device__ void conv_unit(LAS unsigned char* lds, const float* src, int ld, int sn0, int nvalid, int k0, int krows,
;                           bf16_t* dst, int dn0, int Kdst, int kd0, const float* gs, const float* bs, float* c1, float* c2) {
;     LAS bf16_t* T = (LAS bf16_t*)lds;
;     LAS float* red = (LAS float*)(lds + 9216);
;     const int tid = tidx(), kl = tid >> 3, ng = (tid & 7) * 8;
;     float a1[8], a2[8], wn[8], gn, bn;
; #pragma unroll
;     for (int j = 0; j < 8; ++j) { a1[j] = 0.f; a2[j] = 0.f; }
;     const int nkt = krows / 64;
;     { const int k = k0 + kl; gn = gs ? gs[k] : 1.f; bn = bs ? bs[k] : 0.f;
; #pragma unroll
;       for (int j = 0; j < 8; ++j) wn[j] = (ng + j < nvalid) ? src[(size_t)k * ld + sn0 + ng + j] : 0.f; }
;     for (int kt = 0; kt < nkt; ++kt) {
;         float w[8]; const float g = gn, b = bn;
; #pragma unroll
;         for (int j = 0; j < 8; ++j) w[j] = wn[j];
;         if (kt + 1 < nkt) { const int k = k0 + (kt + 1) * 64 + kl; gn = gs ? gs[k] : 1.f; bn = bs ? bs[k] : 0.f;
; #pragma unroll
;             for (int j = 0; j < 8; ++j) wn[j] = (ng + j < nvalid) ? src[(size_t)k * ld + sn0 + ng + j] : 0.f; }
; #pragma unroll
;         for (int j = 0; j < 8; ++j) { const bf16_t wb = f2bf(w[j] * g); a1[j] += bf2f(wb); a2[j] += b * w[j]; T[(ng + j) * 72 + kl] = wb; }
;         LBAR();
;         { const int n = tid >> 3, ks = (tid & 7) * 8; const u32x4 v = *(const LAS u32x4*)(T + n * 72 + ks);
;           *(u32x4*)(dst + (size_t)(dn0 + n) * Kdst + kd0 + kt * 64 + ks) = v; }
;         LBAR();
;     }
; __device__ void weights_units(LAS unsigned char* lds, KP& P0, int lm0, int li0, int ufirst, int ustride) {
;     ...
;             else { const int j = u - 128; const float* w_out = p.in[21] + (size_t)lm * DM * DM;
;                 conv_unit(lds, w_out, DM, j * 64, 64, 0, 1024, (bf16_t*)(ob + OUT_WOUT), j * 64, 1024, 0, nullptr, nullptr, nullptr, nullptr); }
.LBB0_805:
	v_readlane_b32 s20, v255, 25
	s_mov_b64 s[22:23], s[30:31]
	s_mov_b32 s7, -1
	s_waitcnt lgkmcnt(0)
	s_load_dwordx2 s[24:25], s[22:23], 0xe0
	s_cmp_gt_i32 s53, 63
	s_mov_b64 s[14:15], -1
	v_readlane_b32 s21, v255, 26
	s_cbranch_scc0 .LBB0_815
	s_ashr_i32 s21, s20, 31
	s_lshl_b32 s7, s53, 6
	s_cmpk_gt_u32 s53, 0x7f
	s_cbranch_scc0 .LBB0_810
	s_load_dwordx2 s[14:15], s[22:23], 0xa8
	s_mov_b32 s19, s91
	v_mov_b32_e32 v3, v198
	s_lshl_b64 s[40:41], s[20:21], 22
	s_lshl_b64 s[42:43], s[18:19], 2
	s_waitcnt lgkmcnt(0)
	s_add_u32 s44, s14, s40
	s_waitcnt vmcnt(16)
	v_ashrrev_i32_e32 v16, 3, v3
	v_ashrrev_i32_e32 v17, 31, v16
	s_addc_u32 s45, s15, s41
	v_lshlrev_b32_e32 v0, 3, v3
	v_lshlrev_b64 v[18:19], 12, v[16:17]
	s_add_i32 s90, s7, 0xffffe000
	v_and_b32_e32 v2, 56, v0
	v_lshl_add_u64 v[8:9], s[44:45], 0, v[18:19]
	v_lshl_add_u64 v[8:9], s[90:91], 2, v[8:9]
	v_lshlrev_b32_e32 v0, 2, v2
	s_waitcnt vmcnt(15)
	v_lshl_add_u64 v[12:13], v[8:9], 0, v[0:1]
	s_waitcnt vmcnt(13)
	v_add_u32_e32 v20, s18, v16
	v_ashrrev_i32_e32 v21, 31, v20
	v_lshl_add_u64 v[18:19], s[40:41], 0, v[18:19]
	v_and_b32_e32 v3, 7, v3
	s_add_u32 s14, s14, s42
	v_lshlrev_b64 v[20:21], 11, v[20:21]
	v_lshl_or_b32 v18, v3, 5, v18
	s_addc_u32 s15, s15, s43
	v_lshl_or_b32 v20, v3, 4, v20
	v_lshl_add_u32 v0, v2, 1, 0
	v_lshl_add_u32 v17, v16, 1, 0
	v_mul_lo_u32 v22, v16, s10
	v_mul_u32_u24_e32 v23, 0x90, v2
	v_lshl_add_u64 v[18:19], s[14:15], 0, v[18:19]
	v_lshl_add_u64 v[20:21], s[24:25], 0, v[20:21]
	s_mov_b64 s[14:15], 0x2700100
	v_lshl_add_u64 v[20:21], v[20:21], 0, s[14:15]
	s_mov_b64 s[42:43], 0
	v_add_u32_e32 v17, v17, v23
	v_add_u32_e32 v3, v0, v22
	s_mov_b32 s19, 0xc0000
	s_mov_b64 s[44:45], 0x180
	s_mov_b64 s[14:15], 0x40000
	v_and_b32_e32 v52, 7, v198
	v_lshl_add_u32 v14, v52, 4, v17
	v_lshrrev_b32_e32 v52, 6, v198
	v_lshl_add_u32 v15, v52, 4, v3
	global_load_dwordx4 v[8:11], v[12:13], off
	global_load_dwordx4 v[24:27], v[12:13], off offset:16
	v_lshl_add_u64 v[12:13], v[12:13], 0, s[14:15]
	global_load_dwordx4 v[28:31], v[12:13], off
	global_load_dwordx4 v[32:35], v[12:13], off offset:16
	v_lshl_add_u64 v[12:13], v[12:13], 0, s[14:15]
	global_load_dwordx4 v[36:39], v[12:13], off
	global_load_dwordx4 v[40:43], v[12:13], off offset:16
	v_lshl_add_u64 v[12:13], v[12:13], 0, s[14:15]
	global_load_dwordx4 v[44:47], v[12:13], off
	global_load_dwordx4 v[48:51], v[12:13], off offset:16
	v_lshl_add_u64 v[12:13], v[12:13], 0, s[14:15]
	s_waitcnt vmcnt(6)
	v_cvt_pk_bf16_f32 v8, v8, s0
	v_cvt_pk_bf16_f32 v9, v9, s0
	v_cvt_pk_bf16_f32 v10, v10, s0
	v_cvt_pk_bf16_f32 v11, v11, s0
	v_cvt_pk_bf16_f32 v24, v24, s0
	v_cvt_pk_bf16_f32 v25, v25, s0
	v_cvt_pk_bf16_f32 v26, v26, s0
	v_cvt_pk_bf16_f32 v27, v27, s0
	ds_write_b16 v14, v8
	ds_write_b16 v14, v9 offset:144
	ds_write_b16 v14, v10 offset:288
	ds_write_b16 v14, v11 offset:432
	ds_write_b16 v14, v24 offset:576
	ds_write_b16 v14, v25 offset:720
	ds_write_b16 v14, v26 offset:864
	ds_write_b16 v14, v27 offset:1008
	s_waitcnt lgkmcnt(0)
	s_barrier
	ds_read_b128 v[52:55], v15
	global_load_dwordx4 v[8:11], v[12:13], off
	global_load_dwordx4 v[24:27], v[12:13], off offset:16
	v_lshl_add_u64 v[12:13], v[12:13], 0, s[14:15]
	s_waitcnt lgkmcnt(0)
	global_store_dwordx4 v[20:21], v[52:55], off offset:-256
	s_waitcnt vmcnt(7)
	v_cvt_pk_bf16_f32 v28, v28, s0
	v_cvt_pk_bf16_f32 v29, v29, s0
	v_cvt_pk_bf16_f32 v30, v30, s0
	v_cvt_pk_bf16_f32 v31, v31, s0
	v_cvt_pk_bf16_f32 v32, v32, s0
	v_cvt_pk_bf16_f32 v33, v33, s0
	v_cvt_pk_bf16_f32 v34, v34, s0
	v_cvt_pk_bf16_f32 v35, v35, s0
	ds_write_b16 v14, v28 offset:9472
	ds_write_b16 v14, v29 offset:9616
	ds_write_b16 v14, v30 offset:9760
	ds_write_b16 v14, v31 offset:9904
	ds_write_b16 v14, v32 offset:10048
	ds_write_b16 v14, v33 offset:10192
	ds_write_b16 v14, v34 offset:10336
	ds_write_b16 v14, v35 offset:10480
	s_waitcnt lgkmcnt(0)
	s_barrier
	ds_read_b128 v[136:139], v15 offset:9472
	global_load_dwordx4 v[28:31], v[12:13], off
	global_load_dwordx4 v[32:35], v[12:13], off offset:16
	v_lshl_add_u64 v[12:13], v[12:13], 0, s[14:15]
	s_waitcnt lgkmcnt(0)
	global_store_dwordx4 v[20:21], v[136:139], off offset:-128
	s_waitcnt vmcnt(8)
	v_cvt_pk_bf16_f32 v36, v36, s0
	v_cvt_pk_bf16_f32 v37, v37, s0
	v_cvt_pk_bf16_f32 v38, v38, s0
	v_cvt_pk_bf16_f32 v39, v39, s0
	v_cvt_pk_bf16_f32 v40, v40, s0
	v_cvt_pk_bf16_f32 v41, v41, s0
	v_cvt_pk_bf16_f32 v42, v42, s0
	v_cvt_pk_bf16_f32 v43, v43, s0
	ds_write_b16 v14, v36
	ds_write_b16 v14, v37 offset:144
	ds_write_b16 v14, v38 offset:288
	ds_write_b16 v14, v39 offset:432
	ds_write_b16 v14, v40 offset:576
	ds_write_b16 v14, v41 offset:720
	ds_write_b16 v14, v42 offset:864
	ds_write_b16 v14, v43 offset:1008
	s_waitcnt lgkmcnt(0)
	s_barrier
	ds_read_b128 v[52:55], v15
	global_load_dwordx4 v[36:39], v[12:13], off
	global_load_dwordx4 v[40:43], v[12:13], off offset:16
	v_lshl_add_u64 v[12:13], v[12:13], 0, s[14:15]
	s_waitcnt lgkmcnt(0)
	global_store_dwordx4 v[20:21], v[52:55], off
	s_waitcnt vmcnt(9)
	v_cvt_pk_bf16_f32 v44, v44, s0
	v_cvt_pk_bf16_f32 v45, v45, s0
	v_cvt_pk_bf16_f32 v46, v46, s0
	v_cvt_pk_bf16_f32 v47, v47, s0
	v_cvt_pk_bf16_f32 v48, v48, s0
	v_cvt_pk_bf16_f32 v49, v49, s0
	v_cvt_pk_bf16_f32 v50, v50, s0
	v_cvt_pk_bf16_f32 v51, v51, s0
	ds_write_b16 v14, v44 offset:9472
	ds_write_b16 v14, v45 offset:9616
	ds_write_b16 v14, v46 offset:9760
	ds_write_b16 v14, v47 offset:9904
	ds_write_b16 v14, v48 offset:10048
	ds_write_b16 v14, v49 offset:10192
	ds_write_b16 v14, v50 offset:10336
	ds_write_b16 v14, v51 offset:10480
	s_waitcnt lgkmcnt(0)
	s_barrier
; #define LAS __attribute__((address_space(3)))
; __device__ __forceinline__ bf16_t f2bf(float f) { return (bf16_t)(cvt_pk_bf16(f, 0.f) & 0xffffu); }
; __device__ __forceinline__ float bf2f(bf16_t b) { return __uint_as_float(((unsigned)b) << 16); }
; #define LBAR() do { asm volatile("s_waitcnt lgkmcnt(0)" ::: "memory"); __builtin_amdgcn_s_barrier(); asm volatile("" ::: "memory"); } while (0)
; __device__ void conv_unit(LAS unsigned char* lds, const float* src, int ld, int sn0, int nvalid, int k0, int krows,
;                           bf16_t* dst, int dn0, int Kdst, int kd0, const float* gs, const float* bs, float* c1, float* c2) {
;     ...
;     for (int kt = 0; kt < nkt; ++kt) {
;         float w[8]; const float g = gn, b = bn;
; #pragma unroll
;         for (int j = 0; j < 8; ++j) w[j] = wn[j];
;         if (kt + 1 < nkt) { const int k = k0 + (kt + 1) * 64 + kl; gn = gs ? gs[k] : 1.f; bn = bs ? bs[k] : 0.f;
; #pragma unroll
;             for (int j = 0; j < 8; ++j) wn[j] = (ng + j < nvalid) ? src[(size_t)k * ld + sn0 + ng + j] : 0.f; }
; #pragma unroll
;         for (int j = 0; j < 8; ++j) { const bf16_t wb = f2bf(w[j] * g); a1[j] += bf2f(wb); a2[j] += b * w[j]; T[(ng + j) * 72 + kl] = wb; }
;         LBAR();
;         { const int n = tid >> 3, ks = (tid & 7) * 8; const u32x4 v = *(const LAS u32x4*)(T + n * 72 + ks);
;           *(u32x4*)(dst + (size_t)(dn0 + n) * Kdst + kd0 + kt * 64 + ks) = v; }
;         LBAR();
;     }
	ds_read_b128 v[136:139], v15 offset:9472
	global_load_dwordx4 v[44:47], v[12:13], off
	global_load_dwordx4 v[48:51], v[12:13], off offset:16
	v_lshl_add_u64 v[12:13], v[12:13], 0, s[14:15]
	s_waitcnt lgkmcnt(0)
	global_store_dwordx4 v[20:21], v[136:139], off offset:128
	s_waitcnt vmcnt(10)
	v_cvt_pk_bf16_f32 v8, v8, s0
	v_cvt_pk_bf16_f32 v9, v9, s0
	v_cvt_pk_bf16_f32 v10, v10, s0
	v_cvt_pk_bf16_f32 v11, v11, s0
	v_cvt_pk_bf16_f32 v24, v24, s0
	v_cvt_pk_bf16_f32 v25, v25, s0
	v_cvt_pk_bf16_f32 v26, v26, s0
	v_cvt_pk_bf16_f32 v27, v27, s0
	ds_write_b16 v14, v8
	ds_write_b16 v14, v9 offset:144
	ds_write_b16 v14, v10 offset:288
	ds_write_b16 v14, v11 offset:432
	ds_write_b16 v14, v24 offset:576
	ds_write_b16 v14, v25 offset:720
	ds_write_b16 v14, v26 offset:864
	ds_write_b16 v14, v27 offset:1008
	s_waitcnt lgkmcnt(0)
	s_barrier
	ds_read_b128 v[52:55], v15
	global_load_dwordx4 v[8:11], v[12:13], off
	global_load_dwordx4 v[24:27], v[12:13], off offset:16
	v_lshl_add_u64 v[12:13], v[12:13], 0, s[14:15]
	s_waitcnt lgkmcnt(0)
	global_store_dwordx4 v[20:21], v[52:55], off offset:256
	s_waitcnt vmcnt(10)
	v_cvt_pk_bf16_f32 v28, v28, s0
	v_cvt_pk_bf16_f32 v29, v29, s0
	v_cvt_pk_bf16_f32 v30, v30, s0
	v_cvt_pk_bf16_f32 v31, v31, s0
	v_cvt_pk_bf16_f32 v32, v32, s0
	v_cvt_pk_bf16_f32 v33, v33, s0
	v_cvt_pk_bf16_f32 v34, v34, s0
	v_cvt_pk_bf16_f32 v35, v35, s0
	ds_write_b16 v14, v28 offset:9472
	ds_write_b16 v14, v29 offset:9616
	ds_write_b16 v14, v30 offset:9760
	ds_write_b16 v14, v31 offset:9904
	ds_write_b16 v14, v32 offset:10048
	ds_write_b16 v14, v33 offset:10192
	ds_write_b16 v14, v34 offset:10336
	ds_write_b16 v14, v35 offset:10480
	s_waitcnt lgkmcnt(0)
	s_barrier
	ds_read_b128 v[136:139], v15 offset:9472
	global_load_dwordx4 v[28:31], v[12:13], off
	global_load_dwordx4 v[32:35], v[12:13], off offset:16
	v_lshl_add_u64 v[12:13], v[12:13], 0, s[14:15]
	s_waitcnt lgkmcnt(0)
	global_store_dwordx4 v[20:21], v[136:139], off offset:384
	s_waitcnt vmcnt(10)
	v_cvt_pk_bf16_f32 v36, v36, s0
	v_cvt_pk_bf16_f32 v37, v37, s0
	v_cvt_pk_bf16_f32 v38, v38, s0
	v_cvt_pk_bf16_f32 v39, v39, s0
	v_cvt_pk_bf16_f32 v40, v40, s0
	v_cvt_pk_bf16_f32 v41, v41, s0
	v_cvt_pk_bf16_f32 v42, v42, s0
	v_cvt_pk_bf16_f32 v43, v43, s0
	ds_write_b16 v14, v36
	ds_write_b16 v14, v37 offset:144
	ds_write_b16 v14, v38 offset:288
	ds_write_b16 v14, v39 offset:432
	ds_write_b16 v14, v40 offset:576
	ds_write_b16 v14, v41 offset:720
	ds_write_b16 v14, v42 offset:864
	ds_write_b16 v14, v43 offset:1008
	s_waitcnt lgkmcnt(0)
	s_barrier
	ds_read_b128 v[52:55], v15
	global_load_dwordx4 v[36:39], v[12:13], off
	global_load_dwordx4 v[40:43], v[12:13], off offset:16
	v_lshl_add_u64 v[12:13], v[12:13], 0, s[14:15]
	s_waitcnt lgkmcnt(0)
	global_store_dwordx4 v[20:21], v[52:55], off offset:512
	s_waitcnt vmcnt(10)
	v_cvt_pk_bf16_f32 v44, v44, s0
	v_cvt_pk_bf16_f32 v45, v45, s0
	v_cvt_pk_bf16_f32 v46, v46, s0
	v_cvt_pk_bf16_f32 v47, v47, s0
	v_cvt_pk_bf16_f32 v48, v48, s0
	v_cvt_pk_bf16_f32 v49, v49, s0
	v_cvt_pk_bf16_f32 v50, v50, s0
	v_cvt_pk_bf16_f32 v51, v51, s0
	ds_write_b16 v14, v44 offset:9472
	ds_write_b16 v14, v45 offset:9616
	ds_write_b16 v14, v46 offset:9760
	ds_write_b16 v14, v47 offset:9904
	ds_write_b16 v14, v48 offset:10048
	ds_write_b16 v14, v49 offset:10192
	ds_write_b16 v14, v50 offset:10336
	ds_write_b16 v14, v51 offset:10480
	s_waitcnt lgkmcnt(0)
	s_barrier
	ds_read_b128 v[136:139], v15 offset:9472
	global_load_dwordx4 v[44:47], v[12:13], off
	global_load_dwordx4 v[48:51], v[12:13], off offset:16
	v_lshl_add_u64 v[12:13], v[12:13], 0, s[14:15]
	s_waitcnt lgkmcnt(0)
	global_store_dwordx4 v[20:21], v[136:139], off offset:640
	s_waitcnt vmcnt(10)
	v_cvt_pk_bf16_f32 v8, v8, s0
	v_cvt_pk_bf16_f32 v9, v9, s0
	v_cvt_pk_bf16_f32 v10, v10, s0
	v_cvt_pk_bf16_f32 v11, v11, s0
	v_cvt_pk_bf16_f32 v24, v24, s0
	v_cvt_pk_bf16_f32 v25, v25, s0
	v_cvt_pk_bf16_f32 v26, v26, s0
	v_cvt_pk_bf16_f32 v27, v27, s0
	ds_write_b16 v14, v8
	ds_write_b16 v14, v9 offset:144
	ds_write_b16 v14, v10 offset:288
	ds_write_b16 v14, v11 offset:432
	ds_write_b16 v14, v24 offset:576
	ds_write_b16 v14, v25 offset:720
	ds_write_b16 v14, v26 offset:864
	ds_write_b16 v14, v27 offset:1008
	s_waitcnt lgkmcnt(0)
	s_barrier
	ds_read_b128 v[52:55], v15
	global_load_dwordx4 v[8:11], v[12:13], off
	global_load_dwordx4 v[24:27], v[12:13], off offset:16
	v_lshl_add_u64 v[12:13], v[12:13], 0, s[14:15]
	s_waitcnt lgkmcnt(0)
	global_store_dwordx4 v[20:21], v[52:55], off offset:768
	s_waitcnt vmcnt(10)
	v_cvt_pk_bf16_f32 v28, v28, s0
	v_cvt_pk_bf16_f32 v29, v29, s0
	v_cvt_pk_bf16_f32 v30, v30, s0
	v_cvt_pk_bf16_f32 v31, v31, s0
	v_cvt_pk_bf16_f32 v32, v32, s0
	v_cvt_pk_bf16_f32 v33, v33, s0
	v_cvt_pk_bf16_f32 v34, v34, s0
	v_cvt_pk_bf16_f32 v35, v35, s0
	ds_write_b16 v14, v28 offset:9472
	ds_write_b16 v14, v29 offset:9616
	ds_write_b16 v14, v30 offset:9760
	ds_write_b16 v14, v31 offset:9904
	ds_write_b16 v14, v32 offset:10048
	ds_write_b16 v14, v33 offset:10192
	ds_write_b16 v14, v34 offset:10336
	ds_write_b16 v14, v35 offset:10480
	s_waitcnt lgkmcnt(0)
	s_barrier
	ds_read_b128 v[136:139], v15 offset:9472
	global_load_dwordx4 v[28:31], v[12:13], off
	global_load_dwordx4 v[32:35], v[12:13], off offset:16
	v_lshl_add_u64 v[12:13], v[12:13], 0, s[14:15]
	s_waitcnt lgkmcnt(0)
	global_store_dwordx4 v[20:21], v[136:139], off offset:896
	s_waitcnt vmcnt(10)
	v_cvt_pk_bf16_f32 v36, v36, s0
	v_cvt_pk_bf16_f32 v37, v37, s0
	v_cvt_pk_bf16_f32 v38, v38, s0
	v_cvt_pk_bf16_f32 v39, v39, s0
	v_cvt_pk_bf16_f32 v40, v40, s0
	v_cvt_pk_bf16_f32 v41, v41, s0
	v_cvt_pk_bf16_f32 v42, v42, s0
	v_cvt_pk_bf16_f32 v43, v43, s0
	ds_write_b16 v14, v36
	ds_write_b16 v14, v37 offset:144
	ds_write_b16 v14, v38 offset:288
	ds_write_b16 v14, v39 offset:432
	ds_write_b16 v14, v40 offset:576
	ds_write_b16 v14, v41 offset:720
	ds_write_b16 v14, v42 offset:864
	ds_write_b16 v14, v43 offset:1008
	s_waitcnt lgkmcnt(0)
	s_barrier
; #define LAS __attribute__((address_space(3)))
; __device__ __forceinline__ bf16_t f2bf(float f) { return (bf16_t)(cvt_pk_bf16(f, 0.f) & 0xffffu); }
; __device__ __forceinline__ float bf2f(bf16_t b) { return __uint_as_float(((unsigned)b) << 16); }
; #define LBAR() do { asm volatile("s_waitcnt lgkmcnt(0)" ::: "memory"); __builtin_amdgcn_s_barrier(); asm volatile("" ::: "memory"); } while (0)
; __device__ void conv_unit(LAS unsigned char* lds, const float* src, int ld, int sn0, int nvalid, int k0, int krows,
;                           bf16_t* dst, int dn0, int Kdst, int kd0, const float* gs, const float* bs, float* c1, float* c2) {
;     ...
;     for (int kt = 0; kt < nkt; ++kt) {
;         float w[8]; const float g = gn, b = bn;
; #pragma unroll
;         for (int j = 0; j < 8; ++j) w[j] = wn[j];
;         if (kt + 1 < nkt) { const int k = k0 + (kt + 1) * 64 + kl; gn = gs ? gs[k] : 1.f; bn = bs ? bs[k] : 0.f;
; #pragma unroll
;             for (int j = 0; j < 8; ++j) wn[j] = (ng + j < nvalid) ? src[(size_t)k * ld + sn0 + ng + j] : 0.f; }
; #pragma unroll
;         for (int j = 0; j < 8; ++j) { const bf16_t wb = f2bf(w[j] * g); a1[j] += bf2f(wb); a2[j] += b * w[j]; T[(ng + j) * 72 + kl] = wb; }
;         LBAR();
;         { const int n = tid >> 3, ks = (tid & 7) * 8; const u32x4 v = *(const LAS u32x4*)(T + n * 72 + ks);
;           *(u32x4*)(dst + (size_t)(dn0 + n) * Kdst + kd0 + kt * 64 + ks) = v; }
;         LBAR();
;     }
; __device__ void weights_units(LAS unsigned char* lds, KP& P0, int lm0, int li0, int ufirst, int ustride) {
;     ...
;             else if (u < 128) { const int j = (u - 64) & 15, kq = (u - 64) >> 4; const float* w2 = p.in[25] + (size_t)lm * DFF * DM;
;                 conv_unit(lds, w2, DM, j * 64, 64, kq * 1024, 1024, (bf16_t*)(ob + OUT_W2), j * 64, DFF, kq * 1024, nullptr, nullptr, nullptr, nullptr); }
	ds_read_b128 v[52:55], v15
	global_load_dwordx4 v[36:39], v[12:13], off
	global_load_dwordx4 v[40:43], v[12:13], off offset:16
	v_lshl_add_u64 v[12:13], v[12:13], 0, s[14:15]
	s_waitcnt lgkmcnt(0)
	global_store_dwordx4 v[20:21], v[52:55], off offset:1024
	s_waitcnt vmcnt(10)
	v_cvt_pk_bf16_f32 v44, v44, s0
	v_cvt_pk_bf16_f32 v45, v45, s0
	v_cvt_pk_bf16_f32 v46, v46, s0
	v_cvt_pk_bf16_f32 v47, v47, s0
	v_cvt_pk_bf16_f32 v48, v48, s0
	v_cvt_pk_bf16_f32 v49, v49, s0
	v_cvt_pk_bf16_f32 v50, v50, s0
	v_cvt_pk_bf16_f32 v51, v51, s0
	ds_write_b16 v14, v44 offset:9472
	ds_write_b16 v14, v45 offset:9616
	ds_write_b16 v14, v46 offset:9760
	ds_write_b16 v14, v47 offset:9904
	ds_write_b16 v14, v48 offset:10048
	ds_write_b16 v14, v49 offset:10192
	ds_write_b16 v14, v50 offset:10336
	ds_write_b16 v14, v51 offset:10480
	s_waitcnt lgkmcnt(0)
	s_barrier
	ds_read_b128 v[136:139], v15 offset:9472
	global_load_dwordx4 v[44:47], v[12:13], off
	global_load_dwordx4 v[48:51], v[12:13], off offset:16
	v_lshl_add_u64 v[12:13], v[12:13], 0, s[14:15]
	s_waitcnt lgkmcnt(0)
	global_store_dwordx4 v[20:21], v[136:139], off offset:1152
	s_waitcnt vmcnt(10)
	v_cvt_pk_bf16_f32 v8, v8, s0
	v_cvt_pk_bf16_f32 v9, v9, s0
	v_cvt_pk_bf16_f32 v10, v10, s0
	v_cvt_pk_bf16_f32 v11, v11, s0
	v_cvt_pk_bf16_f32 v24, v24, s0
	v_cvt_pk_bf16_f32 v25, v25, s0
	v_cvt_pk_bf16_f32 v26, v26, s0
	v_cvt_pk_bf16_f32 v27, v27, s0
	ds_write_b16 v14, v8
	ds_write_b16 v14, v9 offset:144
	ds_write_b16 v14, v10 offset:288
	ds_write_b16 v14, v11 offset:432
	ds_write_b16 v14, v24 offset:576
	ds_write_b16 v14, v25 offset:720
	ds_write_b16 v14, v26 offset:864
	ds_write_b16 v14, v27 offset:1008
	s_waitcnt lgkmcnt(0)
	s_barrier
	ds_read_b128 v[52:55], v15
	s_waitcnt lgkmcnt(0)
	global_store_dwordx4 v[20:21], v[52:55], off offset:1280
	s_waitcnt vmcnt(8)
	v_cvt_pk_bf16_f32 v28, v28, s0
	v_cvt_pk_bf16_f32 v29, v29, s0
	v_cvt_pk_bf16_f32 v30, v30, s0
	v_cvt_pk_bf16_f32 v31, v31, s0
	v_cvt_pk_bf16_f32 v32, v32, s0
	v_cvt_pk_bf16_f32 v33, v33, s0
	v_cvt_pk_bf16_f32 v34, v34, s0
	v_cvt_pk_bf16_f32 v35, v35, s0
	ds_write_b16 v14, v28 offset:9472
	ds_write_b16 v14, v29 offset:9616
	ds_write_b16 v14, v30 offset:9760
	ds_write_b16 v14, v31 offset:9904
	ds_write_b16 v14, v32 offset:10048
	ds_write_b16 v14, v33 offset:10192
	ds_write_b16 v14, v34 offset:10336
	ds_write_b16 v14, v35 offset:10480
	s_waitcnt lgkmcnt(0)
	s_barrier
	ds_read_b128 v[136:139], v15 offset:9472
	s_waitcnt lgkmcnt(0)
	global_store_dwordx4 v[20:21], v[136:139], off offset:1408
	s_waitcnt vmcnt(6)
	v_cvt_pk_bf16_f32 v36, v36, s0
	v_cvt_pk_bf16_f32 v37, v37, s0
	v_cvt_pk_bf16_f32 v38, v38, s0
	v_cvt_pk_bf16_f32 v39, v39, s0
	v_cvt_pk_bf16_f32 v40, v40, s0
	v_cvt_pk_bf16_f32 v41, v41, s0
	v_cvt_pk_bf16_f32 v42, v42, s0
	v_cvt_pk_bf16_f32 v43, v43, s0
	ds_write_b16 v14, v36
	ds_write_b16 v14, v37 offset:144
	ds_write_b16 v14, v38 offset:288
	ds_write_b16 v14, v39 offset:432
	ds_write_b16 v14, v40 offset:576
	ds_write_b16 v14, v41 offset:720
	ds_write_b16 v14, v42 offset:864
	ds_write_b16 v14, v43 offset:1008
	s_waitcnt lgkmcnt(0)
	s_barrier
	ds_read_b128 v[52:55], v15
	s_waitcnt lgkmcnt(0)
	global_store_dwordx4 v[20:21], v[52:55], off offset:1536
	s_waitcnt vmcnt(4)
	v_cvt_pk_bf16_f32 v44, v44, s0
	v_cvt_pk_bf16_f32 v45, v45, s0
	v_cvt_pk_bf16_f32 v46, v46, s0
	v_cvt_pk_bf16_f32 v47, v47, s0
	v_cvt_pk_bf16_f32 v48, v48, s0
	v_cvt_pk_bf16_f32 v49, v49, s0
	v_cvt_pk_bf16_f32 v50, v50, s0
	v_cvt_pk_bf16_f32 v51, v51, s0
	ds_write_b16 v14, v44 offset:9472
	ds_write_b16 v14, v45 offset:9616
	ds_write_b16 v14, v46 offset:9760
	ds_write_b16 v14, v47 offset:9904
	ds_write_b16 v14, v48 offset:10048
	ds_write_b16 v14, v49 offset:10192
	ds_write_b16 v14, v50 offset:10336
	ds_write_b16 v14, v51 offset:10480
	s_waitcnt lgkmcnt(0)
	s_barrier
	ds_read_b128 v[136:139], v15 offset:9472
	s_waitcnt lgkmcnt(0)
	global_store_dwordx4 v[20:21], v[136:139], off offset:1664
	s_barrier
	s_mov_b64 s[14:15], 0
.LBB0_810:
	s_and_b64 vcc, exec, s[14:15]
	s_cbranch_vccz .LBB0_814
	s_load_dwordx2 s[42:43], s[22:23], 0xc8
	s_and_b32 s12, s6, 0x1c00
	s_bfe_u32 s15, s6, 0x40006
	s_add_i32 s90, s12, 0xfffff000
	s_lshl_b32 s19, s15, 8
	s_lshl_b64 s[44:45], s[90:91], 1
	s_lshl_b64 s[46:47], s[20:21], 24
	s_waitcnt lgkmcnt(0)
	s_add_u32 s48, s42, s46
	s_addc_u32 s49, s43, s47
	s_and_b32 s14, s7, 0x3c0
	s_and_b32 s7, s7, 0x1c00
	s_waitcnt vmcnt(16)
	v_mov_b32_e32 v18, v198
	s_add_i32 s40, s7, 0xfffff000
	s_lshl_b32 s90, s14, 2
	v_ashrrev_i32_e32 v3, 3, v18
	v_add_u32_e32 v8, s40, v3
	v_ashrrev_i32_e32 v9, 31, v8
	v_lshlrev_b32_e32 v0, 3, v18
	v_lshlrev_b64 v[8:9], 12, v[8:9]
	v_and_b32_e32 v2, 56, v0
	v_lshl_add_u64 v[8:9], s[48:49], 0, v[8:9]
	v_lshl_add_u64 v[8:9], v[8:9], 0, s[90:91]
	v_lshlrev_b32_e32 v0, 2, v2
	s_waitcnt vmcnt(15)
	v_lshl_add_u64 v[12:13], v[8:9], 0, v[0:1]
	s_waitcnt vmcnt(13)
; #define LAS __attribute__((address_space(3)))
; __device__ __forceinline__ bf16_t f2bf(float f) { return (bf16_t)(cvt_pk_bf16(f, 0.f) & 0xffffu); }
; __device__ __forceinline__ float bf2f(bf16_t b) { return __uint_as_float(((unsigned)b) << 16); }
; #define LBAR() do { asm volatile("s_waitcnt lgkmcnt(0)" ::: "memory"); __builtin_amdgcn_s_barrier(); asm volatile("" ::: "memory"); } while (0)
; __device__ void conv_unit(LAS unsigned char* lds, const float* src, int ld, int sn0, int nvalid, int k0, int krows,
;                           bf16_t* dst, int dn0, int Kdst, int kd0, const float* gs, const float* bs, float* c1, float* c2) {
;     ...
;     for (int kt = 0; kt < nkt; ++kt) {
;         float w[8]; const float g = gn, b = bn;
; #pragma unroll
;         for (int j = 0; j < 8; ++j) w[j] = wn[j];
;         if (kt + 1 < nkt) { const int k = k0 + (kt + 1) * 64 + kl; gn = gs ? gs[k] : 1.f; bn = bs ? bs[k] : 0.f;
; #pragma unroll
;             for (int j = 0; j < 8; ++j) wn[j] = (ng + j < nvalid) ? src[(size_t)k * ld + sn0 + ng + j] : 0.f; }
; #pragma unroll
;         for (int j = 0; j < 8; ++j) { const bf16_t wb = f2bf(w[j] * g); a1[j] += bf2f(wb); a2[j] += b * w[j]; T[(ng + j) * 72 + kl] = wb; }
;         LBAR();
;         { const int n = tid >> 3, ks = (tid & 7) * 8; const u32x4 v = *(const LAS u32x4*)(T + n * 72 + ks);
;           *(u32x4*)(dst + (size_t)(dn0 + n) * Kdst + kd0 + kt * 64 + ks) = v; }
;         LBAR();
;     }
	v_and_b32_e32 v20, 7, v18
	v_lshl_add_u32 v18, s15, 6, v3
	v_ashrrev_i32_e32 v19, 31, v18
	v_add_u32_e32 v22, s12, v3
	v_lshlrev_b64 v[18:19], 13, v[18:19]
	v_add_u32_e32 v16, 0xfffff040, v22
	v_lshlrev_b32_e32 v27, 5, v20
	v_lshl_or_b32 v18, v20, 4, v18
	v_add_u32_e32 v20, 0xfffff080, v22
	v_add_u32_e32 v22, 0xfffff0c0, v22
	v_ashrrev_i32_e32 v17, 31, v16
	v_ashrrev_i32_e32 v21, 31, v20
	v_ashrrev_i32_e32 v23, 31, v22
	v_lshlrev_b64 v[16:17], 12, v[16:17]
	s_add_u32 s44, s24, s44
	v_lshlrev_b64 v[20:21], 12, v[20:21]
	v_lshlrev_b64 v[22:23], 12, v[22:23]
	v_lshl_add_u64 v[16:17], s[46:47], 0, v[16:17]
	s_addc_u32 s45, s25, s45
	v_lshl_add_u64 v[20:21], s[46:47], 0, v[20:21]
	v_lshl_add_u64 v[22:23], s[46:47], 0, v[22:23]
	v_lshl_add_u32 v0, v2, 1, 0
	v_lshl_add_u32 v24, v3, 1, 0
	v_mul_lo_u32 v26, v3, s10
	v_mul_u32_u24_e32 v25, 0x90, v2
	v_or3_b32 v16, v16, s19, v27
	v_lshl_add_u64 v[18:19], s[44:45], 0, v[18:19]
	s_mov_b64 s[44:45], 0x3100080
	v_or3_b32 v20, v20, s19, v27
	v_or3_b32 v22, v22, s19, v27
	v_lshl_add_u64 v[16:17], s[42:43], 0, v[16:17]
	v_lshl_add_u64 v[18:19], v[18:19], 0, s[44:45]
	v_lshl_add_u64 v[20:21], s[42:43], 0, v[20:21]
	v_lshl_add_u64 v[22:23], s[42:43], 0, v[22:23]
	s_mov_b64 s[42:43], 0
	v_add_u32_e32 v25, v24, v25
	v_add_u32_e32 v24, v0, v26
	s_mov_b64 s[44:45], 0x180
	s_mov_b64 s[14:15], 0x40000
	v_and_b32_e32 v52, 7, v198
	v_lshl_add_u32 v14, v52, 4, v25
	v_lshrrev_b32_e32 v52, 6, v198
	v_lshl_add_u32 v15, v52, 4, v24
	global_load_dwordx4 v[8:11], v[12:13], off
	global_load_dwordx4 v[20:23], v[12:13], off offset:16
	v_lshl_add_u64 v[12:13], v[12:13], 0, s[14:15]
	global_load_dwordx4 v[28:31], v[12:13], off
	global_load_dwordx4 v[32:35], v[12:13], off offset:16
	v_lshl_add_u64 v[12:13], v[12:13], 0, s[14:15]
	global_load_dwordx4 v[36:39], v[12:13], off
	global_load_dwordx4 v[40:43], v[12:13], off offset:16
	v_lshl_add_u64 v[12:13], v[12:13], 0, s[14:15]
	global_load_dwordx4 v[44:47], v[12:13], off
	global_load_dwordx4 v[48:51], v[12:13], off offset:16
	v_lshl_add_u64 v[12:13], v[12:13], 0, s[14:15]
	s_waitcnt vmcnt(6)
	v_cvt_pk_bf16_f32 v8, v8, s0
	v_cvt_pk_bf16_f32 v9, v9, s0
	v_cvt_pk_bf16_f32 v10, v10, s0
	v_cvt_pk_bf16_f32 v11, v11, s0
	v_cvt_pk_bf16_f32 v20, v20, s0
	v_cvt_pk_bf16_f32 v21, v21, s0
	v_cvt_pk_bf16_f32 v22, v22, s0
	v_cvt_pk_bf16_f32 v23, v23, s0
	ds_write_b16 v14, v8
	ds_write_b16 v14, v9 offset:144
	ds_write_b16 v14, v10 offset:288
	ds_write_b16 v14, v11 offset:432
	ds_write_b16 v14, v20 offset:576
	ds_write_b16 v14, v21 offset:720
	ds_write_b16 v14, v22 offset:864
	ds_write_b16 v14, v23 offset:1008
	s_waitcnt lgkmcnt(0)
	s_barrier
	ds_read_b128 v[52:55], v15
	global_load_dwordx4 v[8:11], v[12:13], off
	global_load_dwordx4 v[20:23], v[12:13], off offset:16
	v_lshl_add_u64 v[12:13], v[12:13], 0, s[14:15]
	s_waitcnt lgkmcnt(0)
	global_store_dwordx4 v[18:19], v[52:55], off offset:-128
	s_waitcnt vmcnt(7)
	v_cvt_pk_bf16_f32 v28, v28, s0
	v_cvt_pk_bf16_f32 v29, v29, s0
	v_cvt_pk_bf16_f32 v30, v30, s0
	v_cvt_pk_bf16_f32 v31, v31, s0
	v_cvt_pk_bf16_f32 v32, v32, s0
	v_cvt_pk_bf16_f32 v33, v33, s0
	v_cvt_pk_bf16_f32 v34, v34, s0
	v_cvt_pk_bf16_f32 v35, v35, s0
	ds_write_b16 v14, v28 offset:9472
	ds_write_b16 v14, v29 offset:9616
	ds_write_b16 v14, v30 offset:9760
	ds_write_b16 v14, v31 offset:9904
	ds_write_b16 v14, v32 offset:10048
	ds_write_b16 v14, v33 offset:10192
	ds_write_b16 v14, v34 offset:10336
	ds_write_b16 v14, v35 offset:10480
	s_waitcnt lgkmcnt(0)
	s_barrier
	ds_read_b128 v[136:139], v15 offset:9472
	global_load_dwordx4 v[28:31], v[12:13], off
	global_load_dwordx4 v[32:35], v[12:13], off offset:16
	v_lshl_add_u64 v[12:13], v[12:13], 0, s[14:15]
	s_waitcnt lgkmcnt(0)
	global_store_dwordx4 v[18:19], v[136:139], off
	s_waitcnt vmcnt(8)
	v_cvt_pk_bf16_f32 v36, v36, s0
	v_cvt_pk_bf16_f32 v37, v37, s0
	v_cvt_pk_bf16_f32 v38, v38, s0
	v_cvt_pk_bf16_f32 v39, v39, s0
	v_cvt_pk_bf16_f32 v40, v40, s0
	v_cvt_pk_bf16_f32 v41, v41, s0
	v_cvt_pk_bf16_f32 v42, v42, s0
	v_cvt_pk_bf16_f32 v43, v43, s0
	ds_write_b16 v14, v36
	ds_write_b16 v14, v37 offset:144
	ds_write_b16 v14, v38 offset:288
	ds_write_b16 v14, v39 offset:432
	ds_write_b16 v14, v40 offset:576
	ds_write_b16 v14, v41 offset:720
	ds_write_b16 v14, v42 offset:864
	ds_write_b16 v14, v43 offset:1008
	s_waitcnt lgkmcnt(0)
	s_barrier
	ds_read_b128 v[52:55], v15
	global_load_dwordx4 v[36:39], v[12:13], off
	global_load_dwordx4 v[40:43], v[12:13], off offset:16
	v_lshl_add_u64 v[12:13], v[12:13], 0, s[14:15]
	s_waitcnt lgkmcnt(0)
	global_store_dwordx4 v[18:19], v[52:55], off offset:128
	s_waitcnt vmcnt(9)
	v_cvt_pk_bf16_f32 v44, v44, s0
	v_cvt_pk_bf16_f32 v45, v45, s0
	v_cvt_pk_bf16_f32 v46, v46, s0
	v_cvt_pk_bf16_f32 v47, v47, s0
	v_cvt_pk_bf16_f32 v48, v48, s0
	v_cvt_pk_bf16_f32 v49, v49, s0
	v_cvt_pk_bf16_f32 v50, v50, s0
	v_cvt_pk_bf16_f32 v51, v51, s0
	ds_write_b16 v14, v44 offset:9472
	ds_write_b16 v14, v45 offset:9616
	ds_write_b16 v14, v46 offset:9760
	ds_write_b16 v14, v47 offset:9904
	ds_write_b16 v14, v48 offset:10048
	ds_write_b16 v14, v49 offset:10192
	ds_write_b16 v14, v50 offset:10336
	ds_write_b16 v14, v51 offset:10480
	s_waitcnt lgkmcnt(0)
	s_barrier
	ds_read_b128 v[136:139], v15 offset:9472
	global_load_dwordx4 v[44:47], v[12:13], off
	global_load_dwordx4 v[48:51], v[12:13], off offset:16
	v_lshl_add_u64 v[12:13], v[12:13], 0, s[14:15]
	s_waitcnt lgkmcnt(0)
	global_store_dwordx4 v[18:19], v[136:139], off offset:256
	s_waitcnt vmcnt(10)
	v_cvt_pk_bf16_f32 v8, v8, s0
	v_cvt_pk_bf16_f32 v9, v9, s0
	v_cvt_pk_bf16_f32 v10, v10, s0
	v_cvt_pk_bf16_f32 v11, v11, s0
	v_cvt_pk_bf16_f32 v20, v20, s0
	v_cvt_pk_bf16_f32 v21, v21, s0
	v_cvt_pk_bf16_f32 v22, v22, s0
	v_cvt_pk_bf16_f32 v23, v23, s0
	ds_write_b16 v14, v8
	ds_write_b16 v14, v9 offset:144
	ds_write_b16 v14, v10 offset:288
	ds_write_b16 v14, v11 offset:432
	ds_write_b16 v14, v20 offset:576
	ds_write_b16 v14, v21 offset:720
	ds_write_b16 v14, v22 offset:864
	ds_write_b16 v14, v23 offset:1008
	s_waitcnt lgkmcnt(0)
	s_barrier
; #define LAS __attribute__((address_space(3)))
; __device__ __forceinline__ bf16_t f2bf(float f) { return (bf16_t)(cvt_pk_bf16(f, 0.f) & 0xffffu); }
; __device__ __forceinline__ float bf2f(bf16_t b) { return __uint_as_float(((unsigned)b) << 16); }
; #define LBAR() do { asm volatile("s_waitcnt lgkmcnt(0)" ::: "memory"); __builtin_amdgcn_s_barrier(); asm volatile("" ::: "memory"); } while (0)
; __device__ void conv_unit(LAS unsigned char* lds, const float* src, int ld, int sn0, int nvalid, int k0, int krows,
;                           bf16_t* dst, int dn0, int Kdst, int kd0, const float* gs, const float* bs, float* c1, float* c2) {
;     ...
;     for (int kt = 0; kt < nkt; ++kt) {
;         float w[8]; const float g = gn, b = bn;
; #pragma unroll
;         for (int j = 0; j < 8; ++j) w[j] = wn[j];
;         if (kt + 1 < nkt) { const int k = k0 + (kt + 1) * 64 + kl; gn = gs ? gs[k] : 1.f; bn = bs ? bs[k] : 0.f;
; #pragma unroll
;             for (int j = 0; j < 8; ++j) wn[j] = (ng + j < nvalid) ? src[(size_t)k * ld + sn0 + ng + j] : 0.f; }
; #pragma unroll
;         for (int j = 0; j < 8; ++j) { const bf16_t wb = f2bf(w[j] * g); a1[j] += bf2f(wb); a2[j] += b * w[j]; T[(ng + j) * 72 + kl] = wb; }
;         LBAR();
;         { const int n = tid >> 3, ks = (tid & 7) * 8; const u32x4 v = *(const LAS u32x4*)(T + n * 72 + ks);
;           *(u32x4*)(dst + (size_t)(dn0 + n) * Kdst + kd0 + kt * 64 + ks) = v; }
;         LBAR();
;     }
	ds_read_b128 v[52:55], v15
	global_load_dwordx4 v[8:11], v[12:13], off
	global_load_dwordx4 v[20:23], v[12:13], off offset:16
	v_lshl_add_u64 v[12:13], v[12:13], 0, s[14:15]
	s_waitcnt lgkmcnt(0)
	global_store_dwordx4 v[18:19], v[52:55], off offset:384
	s_waitcnt vmcnt(10)
	v_cvt_pk_bf16_f32 v28, v28, s0
	v_cvt_pk_bf16_f32 v29, v29, s0
	v_cvt_pk_bf16_f32 v30, v30, s0
	v_cvt_pk_bf16_f32 v31, v31, s0
	v_cvt_pk_bf16_f32 v32, v32, s0
	v_cvt_pk_bf16_f32 v33, v33, s0
	v_cvt_pk_bf16_f32 v34, v34, s0
	v_cvt_pk_bf16_f32 v35, v35, s0
	ds_write_b16 v14, v28 offset:9472
	ds_write_b16 v14, v29 offset:9616
	ds_write_b16 v14, v30 offset:9760
	ds_write_b16 v14, v31 offset:9904
	ds_write_b16 v14, v32 offset:10048
	ds_write_b16 v14, v33 offset:10192
	ds_write_b16 v14, v34 offset:10336
	ds_write_b16 v14, v35 offset:10480
	s_waitcnt lgkmcnt(0)
	s_barrier
	ds_read_b128 v[136:139], v15 offset:9472
	global_load_dwordx4 v[28:31], v[12:13], off
	global_load_dwordx4 v[32:35], v[12:13], off offset:16
	v_lshl_add_u64 v[12:13], v[12:13], 0, s[14:15]
	s_waitcnt lgkmcnt(0)
	global_store_dwordx4 v[18:19], v[136:139], off offset:512
	s_waitcnt vmcnt(10)
	v_cvt_pk_bf16_f32 v36, v36, s0
	v_cvt_pk_bf16_f32 v37, v37, s0
	v_cvt_pk_bf16_f32 v38, v38, s0
	v_cvt_pk_bf16_f32 v39, v39, s0
	v_cvt_pk_bf16_f32 v40, v40, s0
	v_cvt_pk_bf16_f32 v41, v41, s0
	v_cvt_pk_bf16_f32 v42, v42, s0
	v_cvt_pk_bf16_f32 v43, v43, s0
	ds_write_b16 v14, v36
	ds_write_b16 v14, v37 offset:144
	ds_write_b16 v14, v38 offset:288
	ds_write_b16 v14, v39 offset:432
	ds_write_b16 v14, v40 offset:576
	ds_write_b16 v14, v41 offset:720
	ds_write_b16 v14, v42 offset:864
	ds_write_b16 v14, v43 offset:1008
	s_waitcnt lgkmcnt(0)
	s_barrier
	ds_read_b128 v[52:55], v15
	global_load_dwordx4 v[36:39], v[12:13], off
	global_load_dwordx4 v[40:43], v[12:13], off offset:16
	v_lshl_add_u64 v[12:13], v[12:13], 0, s[14:15]
	s_waitcnt lgkmcnt(0)
	global_store_dwordx4 v[18:19], v[52:55], off offset:640
	s_waitcnt vmcnt(10)
	v_cvt_pk_bf16_f32 v44, v44, s0
	v_cvt_pk_bf16_f32 v45, v45, s0
	v_cvt_pk_bf16_f32 v46, v46, s0
	v_cvt_pk_bf16_f32 v47, v47, s0
	v_cvt_pk_bf16_f32 v48, v48, s0
	v_cvt_pk_bf16_f32 v49, v49, s0
	v_cvt_pk_bf16_f32 v50, v50, s0
	v_cvt_pk_bf16_f32 v51, v51, s0
	ds_write_b16 v14, v44 offset:9472
	ds_write_b16 v14, v45 offset:9616
	ds_write_b16 v14, v46 offset:9760
	ds_write_b16 v14, v47 offset:9904
	ds_write_b16 v14, v48 offset:10048
	ds_write_b16 v14, v49 offset:10192
	ds_write_b16 v14, v50 offset:10336
	ds_write_b16 v14, v51 offset:10480
	s_waitcnt lgkmcnt(0)
	s_barrier
	ds_read_b128 v[136:139], v15 offset:9472
	global_load_dwordx4 v[44:47], v[12:13], off
	global_load_dwordx4 v[48:51], v[12:13], off offset:16
	v_lshl_add_u64 v[12:13], v[12:13], 0, s[14:15]
	s_waitcnt lgkmcnt(0)
	global_store_dwordx4 v[18:19], v[136:139], off offset:768
	s_waitcnt vmcnt(10)
	v_cvt_pk_bf16_f32 v8, v8, s0
	v_cvt_pk_bf16_f32 v9, v9, s0
	v_cvt_pk_bf16_f32 v10, v10, s0
	v_cvt_pk_bf16_f32 v11, v11, s0
	v_cvt_pk_bf16_f32 v20, v20, s0
	v_cvt_pk_bf16_f32 v21, v21, s0
	v_cvt_pk_bf16_f32 v22, v22, s0
	v_cvt_pk_bf16_f32 v23, v23, s0
	ds_write_b16 v14, v8
	ds_write_b16 v14, v9 offset:144
	ds_write_b16 v14, v10 offset:288
	ds_write_b16 v14, v11 offset:432
	ds_write_b16 v14, v20 offset:576
	ds_write_b16 v14, v21 offset:720
	ds_write_b16 v14, v22 offset:864
	ds_write_b16 v14, v23 offset:1008
	s_waitcnt lgkmcnt(0)
	s_barrier
	ds_read_b128 v[52:55], v15
	global_load_dwordx4 v[8:11], v[12:13], off
	global_load_dwordx4 v[20:23], v[12:13], off offset:16
	v_lshl_add_u64 v[12:13], v[12:13], 0, s[14:15]
	s_waitcnt lgkmcnt(0)
	global_store_dwordx4 v[18:19], v[52:55], off offset:896
	s_waitcnt vmcnt(10)
	v_cvt_pk_bf16_f32 v28, v28, s0
	v_cvt_pk_bf16_f32 v29, v29, s0
	v_cvt_pk_bf16_f32 v30, v30, s0
	v_cvt_pk_bf16_f32 v31, v31, s0
	v_cvt_pk_bf16_f32 v32, v32, s0
	v_cvt_pk_bf16_f32 v33, v33, s0
	v_cvt_pk_bf16_f32 v34, v34, s0
	v_cvt_pk_bf16_f32 v35, v35, s0
	ds_write_b16 v14, v28 offset:9472
	ds_write_b16 v14, v29 offset:9616
	ds_write_b16 v14, v30 offset:9760
	ds_write_b16 v14, v31 offset:9904
	ds_write_b16 v14, v32 offset:10048
	ds_write_b16 v14, v33 offset:10192
	ds_write_b16 v14, v34 offset:10336
	ds_write_b16 v14, v35 offset:10480
	s_waitcnt lgkmcnt(0)
	s_barrier
; #define LAS __attribute__((address_space(3)))
; __device__ __forceinline__ bf16_t f2bf(float f) { return (bf16_t)(cvt_pk_bf16(f, 0.f) & 0xffffu); }
; __device__ __forceinline__ float bf2f(bf16_t b) { return __uint_as_float(((unsigned)b) << 16); }
; #define LBAR() do { asm volatile("s_waitcnt lgkmcnt(0)" ::: "memory"); __builtin_amdgcn_s_barrier(); asm volatile("" ::: "memory"); } while (0)
; __device__ void conv_unit(LAS unsigned char* lds, const float* src, int ld, int sn0, int nvalid, int k0, int krows,
;                           bf16_t* dst, int dn0, int Kdst, int kd0, const float* gs, const float* bs, float* c1, float* c2) {
;     ...
;     for (int kt = 0; kt < nkt; ++kt) {
;         float w[8]; const float g = gn, b = bn;
; #pragma unroll
;         for (int j = 0; j < 8; ++j) w[j] = wn[j];
;         if (kt + 1 < nkt) { const int k = k0 + (kt + 1) * 64 + kl; gn = gs ? gs[k] : 1.f; bn = bs ? bs[k] : 0.f;
; #pragma unroll
;             for (int j = 0; j < 8; ++j) wn[j] = (ng + j < nvalid) ? src[(size_t)k * ld + sn0 + ng + j] : 0.f; }
; #pragma unroll
;         for (int j = 0; j < 8; ++j) { const bf16_t wb = f2bf(w[j] * g); a1[j] += bf2f(wb); a2[j] += b * w[j]; T[(ng + j) * 72 + kl] = wb; }
;         LBAR();
;         { const int n = tid >> 3, ks = (tid & 7) * 8; const u32x4 v = *(const LAS u32x4*)(T + n * 72 + ks);
;           *(u32x4*)(dst + (size_t)(dn0 + n) * Kdst + kd0 + kt * 64 + ks) = v; }
;         LBAR();
;     }
	ds_read_b128 v[136:139], v15 offset:9472
	global_load_dwordx4 v[28:31], v[12:13], off
	global_load_dwordx4 v[32:35], v[12:13], off offset:16
	v_lshl_add_u64 v[12:13], v[12:13], 0, s[14:15]
	s_waitcnt lgkmcnt(0)
	global_store_dwordx4 v[18:19], v[136:139], off offset:1024
	s_waitcnt vmcnt(10)
	v_cvt_pk_bf16_f32 v36, v36, s0
	v_cvt_pk_bf16_f32 v37, v37, s0
	v_cvt_pk_bf16_f32 v38, v38, s0
	v_cvt_pk_bf16_f32 v39, v39, s0
	v_cvt_pk_bf16_f32 v40, v40, s0
	v_cvt_pk_bf16_f32 v41, v41, s0
	v_cvt_pk_bf16_f32 v42, v42, s0
	v_cvt_pk_bf16_f32 v43, v43, s0
	ds_write_b16 v14, v36
	ds_write_b16 v14, v37 offset:144
	ds_write_b16 v14, v38 offset:288
	ds_write_b16 v14, v39 offset:432
	ds_write_b16 v14, v40 offset:576
	ds_write_b16 v14, v41 offset:720
	ds_write_b16 v14, v42 offset:864
	ds_write_b16 v14, v43 offset:1008
	s_waitcnt lgkmcnt(0)
	s_barrier
	ds_read_b128 v[52:55], v15
	global_load_dwordx4 v[36:39], v[12:13], off
	global_load_dwordx4 v[40:43], v[12:13], off offset:16
	v_lshl_add_u64 v[12:13], v[12:13], 0, s[14:15]
	s_waitcnt lgkmcnt(0)
	global_store_dwordx4 v[18:19], v[52:55], off offset:1152
	s_waitcnt vmcnt(10)
	v_cvt_pk_bf16_f32 v44, v44, s0
	v_cvt_pk_bf16_f32 v45, v45, s0
	v_cvt_pk_bf16_f32 v46, v46, s0
	v_cvt_pk_bf16_f32 v47, v47, s0
	v_cvt_pk_bf16_f32 v48, v48, s0
	v_cvt_pk_bf16_f32 v49, v49, s0
	v_cvt_pk_bf16_f32 v50, v50, s0
	v_cvt_pk_bf16_f32 v51, v51, s0
	ds_write_b16 v14, v44 offset:9472
	ds_write_b16 v14, v45 offset:9616
	ds_write_b16 v14, v46 offset:9760
	ds_write_b16 v14, v47 offset:9904
	ds_write_b16 v14, v48 offset:10048
	ds_write_b16 v14, v49 offset:10192
	ds_write_b16 v14, v50 offset:10336
	ds_write_b16 v14, v51 offset:10480
	s_waitcnt lgkmcnt(0)
	s_barrier
	ds_read_b128 v[136:139], v15 offset:9472
	global_load_dwordx4 v[44:47], v[12:13], off
	global_load_dwordx4 v[48:51], v[12:13], off offset:16
	v_lshl_add_u64 v[12:13], v[12:13], 0, s[14:15]
	s_waitcnt lgkmcnt(0)
	global_store_dwordx4 v[18:19], v[136:139], off offset:1280
	s_waitcnt vmcnt(10)
	v_cvt_pk_bf16_f32 v8, v8, s0
	v_cvt_pk_bf16_f32 v9, v9, s0
	v_cvt_pk_bf16_f32 v10, v10, s0
	v_cvt_pk_bf16_f32 v11, v11, s0
	v_cvt_pk_bf16_f32 v20, v20, s0
	v_cvt_pk_bf16_f32 v21, v21, s0
	v_cvt_pk_bf16_f32 v22, v22, s0
	v_cvt_pk_bf16_f32 v23, v23, s0
	ds_write_b16 v14, v8
	ds_write_b16 v14, v9 offset:144
	ds_write_b16 v14, v10 offset:288
	ds_write_b16 v14, v11 offset:432
	ds_write_b16 v14, v20 offset:576
	ds_write_b16 v14, v21 offset:720
	ds_write_b16 v14, v22 offset:864
	ds_write_b16 v14, v23 offset:1008
	s_waitcnt lgkmcnt(0)
	s_barrier
	ds_read_b128 v[52:55], v15
	s_waitcnt lgkmcnt(0)
	global_store_dwordx4 v[18:19], v[52:55], off offset:1408
	s_waitcnt vmcnt(8)
	v_cvt_pk_bf16_f32 v28, v28, s0
	v_cvt_pk_bf16_f32 v29, v29, s0
	v_cvt_pk_bf16_f32 v30, v30, s0
	v_cvt_pk_bf16_f32 v31, v31, s0
	v_cvt_pk_bf16_f32 v32, v32, s0
	v_cvt_pk_bf16_f32 v33, v33, s0
	v_cvt_pk_bf16_f32 v34, v34, s0
	v_cvt_pk_bf16_f32 v35, v35, s0
	ds_write_b16 v14, v28 offset:9472
	ds_write_b16 v14, v29 offset:9616
	ds_write_b16 v14, v30 offset:9760
	ds_write_b16 v14, v31 offset:9904
	ds_write_b16 v14, v32 offset:10048
	ds_write_b16 v14, v33 offset:10192
	ds_write_b16 v14, v34 offset:10336
	ds_write_b16 v14, v35 offset:10480
	s_waitcnt lgkmcnt(0)
	s_barrier
	ds_read_b128 v[136:139], v15 offset:9472
	s_waitcnt lgkmcnt(0)
	global_store_dwordx4 v[18:19], v[136:139], off offset:1536
	s_waitcnt vmcnt(6)
	v_cvt_pk_bf16_f32 v36, v36, s0
	v_cvt_pk_bf16_f32 v37, v37, s0
	v_cvt_pk_bf16_f32 v38, v38, s0
	v_cvt_pk_bf16_f32 v39, v39, s0
	v_cvt_pk_bf16_f32 v40, v40, s0
	v_cvt_pk_bf16_f32 v41, v41, s0
	v_cvt_pk_bf16_f32 v42, v42, s0
	v_cvt_pk_bf16_f32 v43, v43, s0
	ds_write_b16 v14, v36
	ds_write_b16 v14, v37 offset:144
	ds_write_b16 v14, v38 offset:288
	ds_write_b16 v14, v39 offset:432
	ds_write_b16 v14, v40 offset:576
	ds_write_b16 v14, v41 offset:720
	ds_write_b16 v14, v42 offset:864
	ds_write_b16 v14, v43 offset:1008
	s_waitcnt lgkmcnt(0)
	s_barrier
	ds_read_b128 v[52:55], v15
	s_waitcnt lgkmcnt(0)
	global_store_dwordx4 v[18:19], v[52:55], off offset:1664
	s_waitcnt vmcnt(4)
	v_cvt_pk_bf16_f32 v44, v44, s0
	v_cvt_pk_bf16_f32 v45, v45, s0
	v_cvt_pk_bf16_f32 v46, v46, s0
	v_cvt_pk_bf16_f32 v47, v47, s0
	v_cvt_pk_bf16_f32 v48, v48, s0
	v_cvt_pk_bf16_f32 v49, v49, s0
	v_cvt_pk_bf16_f32 v50, v50, s0
	v_cvt_pk_bf16_f32 v51, v51, s0
	ds_write_b16 v14, v44 offset:9472
	ds_write_b16 v14, v45 offset:9616
	ds_write_b16 v14, v46 offset:9760
	ds_write_b16 v14, v47 offset:9904
	ds_write_b16 v14, v48 offset:10048
	ds_write_b16 v14, v49 offset:10192
	ds_write_b16 v14, v50 offset:10336
	ds_write_b16 v14, v51 offset:10480
	s_waitcnt lgkmcnt(0)
	s_barrier
	ds_read_b128 v[136:139], v15 offset:9472
	s_waitcnt lgkmcnt(0)
	global_store_dwordx4 v[18:19], v[136:139], off offset:1792
	s_barrier

; #define LAS __attribute__((address_space(3)))
; __device__ __forceinline__ bf16_t f2bf(float f) { return (bf16_t)(cvt_pk_bf16(f, 0.f) & 0xffffu); }
; __device__ __forceinline__ float bf2f(bf16_t b) { return __uint_as_float(((unsigned)b) << 16); }
; #define LBAR() do { asm volatile("s_waitcnt lgkmcnt(0)" ::: "memory"); __builtin_amdgcn_s_barrier(); asm volatile("" ::: "memory"); } while (0)
; __device__ void conv_unit(LAS unsigned char* lds, const float* src, int ld, int sn0, int nvalid, int k0, int krows,
;                           bf16_t* dst, int dn0, int Kdst, int kd0, const float* gs, const float* bs, float* c1, float* c2) {
;     ...
;     { const int k = k0 + kl; gn = gs ? gs[k] : 1.f; bn = bs ? bs[k] : 0.f;
; #pragma unroll
;       for (int j = 0; j < 8; ++j) wn[j] = (ng + j < nvalid) ? src[(size_t)k * ld + sn0 + ng + j] : 0.f; }
;     for (int kt = 0; kt < nkt; ++kt) {
;         float w[8]; const float g = gn, b = bn;
; #pragma unroll
;         for (int j = 0; j < 8; ++j) w[j] = wn[j];
;         if (kt + 1 < nkt) { const int k = k0 + (kt + 1) * 64 + kl; gn = gs ? gs[k] : 1.f; bn = bs ? bs[k] : 0.f;
; #pragma unroll
;             for (int j = 0; j < 8; ++j) wn[j] = (ng + j < nvalid) ? src[(size_t)k * ld + sn0 + ng + j] : 0.f; }
; #pragma unroll
;         for (int j = 0; j < 8; ++j) { const bf16_t wb = f2bf(w[j] * g); a1[j] += bf2f(wb); a2[j] += b * w[j]; T[(ng + j) * 72 + kl] = wb; }
;         LBAR();
;         { const int n = tid >> 3, ks = (tid & 7) * 8; const u32x4 v = *(const LAS u32x4*)(T + n * 72 + ks);
;           *(u32x4*)(dst + (size_t)(dn0 + n) * Kdst + kd0 + kt * 64 + ks) = v; }
;         LBAR();
;     }
; __device__ void weights_units(LAS unsigned char* lds, KP& P0, int lm0, int li0, int ufirst, int ustride) {
;     ...
;             if (u < 64) { const float* w1 = p.in[24] + (size_t)lm * DM * DFF;
;                 conv_unit(lds, w1, DFF, u * 64, 64, 0, 1024, (bf16_t*)(ob + OUT_W1), u * 64, 1024, 0, p.in[22] + (size_t)lm * DM, p.in[23] + (size_t)lm * DM, (float*)(ws + WS_C1MLP), (float*)(ws + WS_C2MLP)); }
.LBB0_821:
	s_lshl_b64 s[14:15], s[20:21], 24
	s_waitcnt lgkmcnt(0)
	s_add_u32 s54, s50, s14
	s_addc_u32 s55, s51, s15
	s_lshl_b32 s44, s53, 6
	s_add_u32 s24, s24, 0x2900000
	v_lshlrev_b32_e32 v0, 3, v31
	v_lshlrev_b64 v[8:9], 14, v[32:33]
	s_addc_u32 s25, s25, 0
	v_and_b32_e32 v34, 56, v0
	s_ashr_i32 s45, s44, 31
	v_lshl_add_u64 v[10:11], s[54:55], 0, v[8:9]
	v_lshl_add_u64 v[10:11], s[44:45], 2, v[10:11]
	v_lshlrev_b32_e32 v0, 2, v34
	v_lshl_add_u64 v[10:11], v[10:11], 0, v[0:1]
	global_load_dwordx4 v[16:19], v[10:11], off offset:16
	global_load_dwordx4 v[20:23], v[10:11], off
	s_ashr_i32 s7, s6, 31
	v_add_u32_e32 v10, s6, v32
	s_lshl_b64 s[54:55], s[6:7], 2
	v_ashrrev_i32_e32 v11, 31, v10
	s_lshl_b64 s[20:21], s[20:21], 12
	v_lshlrev_b64 v[10:11], 11, v[10:11]
	v_and_b32_e32 v15, 7, v31
	v_lshl_add_u64 v[8:9], s[14:15], 0, v[8:9]
	s_add_u32 s14, s50, s54
	v_lshl_or_b32 v10, v15, 4, v10
	v_lshl_or_b32 v8, v15, 5, v8
	s_addc_u32 s15, s51, s55
	v_lshl_add_u32 v3, v34, 1, 0
	v_lshl_add_u32 v12, v32, 1, 0
	v_mul_lo_u32 v13, v32, s10
	v_mul_u32_u24_e32 v14, 0x90, v34
	v_lshl_add_u64 v[44:45], s[24:25], 0, v[10:11]
	v_lshl_add_u64 v[10:11], v[32:33], 2, s[20:21]
	v_lshl_add_u64 v[8:9], s[14:15], 0, v[8:9]
	s_mov_b64 s[14:15], 0x100010
	s_waitcnt vmcnt(7)
	v_lshl_add_u64 v[48:49], s[40:41], 0, v[10:11]
	v_lshl_add_u64 v[52:53], v[8:9], 0, s[14:15]
	v_lshl_add_u64 v[54:55], s[42:43], 0, v[10:11]
	s_mov_b64 s[20:21], 0x100
	v_add_u32_e32 v35, v12, v14
	v_add_u32_e32 v33, v3, v13
	v_mov_b32_e32 v3, v2
	v_mov_b32_e32 v24, v2
	v_mov_b32_e32 v25, v2
	v_mov_b32_e32 v26, v2
	v_mov_b32_e32 v27, v2
	v_mov_b32_e32 v28, v2
	v_mov_b32_e32 v29, v2
	v_mov_b32_e32 v50, v2
	v_mov_b32_e32 v51, v2
	v_mov_b32_e32 v46, v2
	v_mov_b32_e32 v47, v2
	v_mov_b32_e32 v42, v2
	v_mov_b32_e32 v43, v2
	v_mov_b32_e32 v40, v2
	v_mov_b32_e32 v41, v2
	v_and_b32_e32 v88, 7, v198
	v_lshl_add_u32 v92, v88, 4, v35
	v_lshrrev_b32_e32 v88, 6, v198
	v_lshl_add_u32 v93, v88, 4, v33
	global_load_dword v144, v[48:49], off offset:256
	global_load_dword v146, v[54:55], off offset:256
	global_load_dwordx4 v[140:143], v[52:53], off
	global_load_dwordx4 v[136:139], v[52:53], off offset:-16
	v_lshl_add_u64 v[52:53], v[52:53], 0, s[88:89]
	global_load_dword v156, v[48:49], off offset:512
	global_load_dword v158, v[54:55], off offset:512
	global_load_dwordx4 v[152:155], v[52:53], off
	global_load_dwordx4 v[148:151], v[52:53], off offset:-16
	v_lshl_add_u64 v[52:53], v[52:53], 0, s[88:89]
	global_load_dword v56, v[48:49], off offset:768
	global_load_dword v30, v[54:55], off offset:768
	global_load_dwordx4 v[8:11], v[52:53], off
	global_load_dwordx4 v[12:15], v[52:53], off offset:-16
	v_lshl_add_u64 v[52:53], v[52:53], 0, s[88:89]
	s_waitcnt vmcnt(12)
	v_pk_mul_f32 v[160:161], v[20:21], v[36:37] op_sel_hi:[1,0]
	v_cvt_pk_bf16_f32 v162, v160, v161
	v_pk_fma_f32 v[2:3], v[20:21], v[38:39], v[2:3] op_sel_hi:[1,0,1]
	v_lshlrev_b32_e32 v164, 16, v162
	v_and_b32_e32 v165, 0xffff0000, v162
	v_lshrrev_b32_e32 v163, 16, v162
	ds_write_b16 v92, v162
	ds_write_b16 v92, v163 offset:144
	v_pk_add_f32 v[50:51], v[50:51], v[164:165]
	v_pk_mul_f32 v[166:167], v[22:23], v[36:37] op_sel_hi:[1,0]
	v_cvt_pk_bf16_f32 v134, v166, v167
	v_pk_fma_f32 v[24:25], v[22:23], v[38:39], v[24:25] op_sel_hi:[1,0,1]
	v_lshlrev_b32_e32 v58, 16, v134
	v_and_b32_e32 v59, 0xffff0000, v134
	v_lshrrev_b32_e32 v135, 16, v134
	ds_write_b16 v92, v134 offset:288
	ds_write_b16 v92, v135 offset:432
	v_pk_add_f32 v[46:47], v[46:47], v[58:59]
	v_pk_mul_f32 v[160:161], v[16:17], v[36:37] op_sel_hi:[1,0]
	v_cvt_pk_bf16_f32 v162, v160, v161
	v_pk_fma_f32 v[26:27], v[16:17], v[38:39], v[26:27] op_sel_hi:[1,0,1]
	v_lshlrev_b32_e32 v164, 16, v162
	v_and_b32_e32 v165, 0xffff0000, v162
	v_lshrrev_b32_e32 v163, 16, v162
	ds_write_b16 v92, v162 offset:576
	ds_write_b16 v92, v163 offset:720
	v_pk_add_f32 v[42:43], v[42:43], v[164:165]
	v_pk_mul_f32 v[166:167], v[18:19], v[36:37] op_sel_hi:[1,0]
	v_cvt_pk_bf16_f32 v134, v166, v167
	v_pk_fma_f32 v[28:29], v[18:19], v[38:39], v[28:29] op_sel_hi:[1,0,1]
	v_lshlrev_b32_e32 v58, 16, v134
	v_and_b32_e32 v59, 0xffff0000, v134
	v_lshrrev_b32_e32 v135, 16, v134
	ds_write_b16 v92, v134 offset:864
	ds_write_b16 v92, v135 offset:1008
	v_pk_add_f32 v[40:41], v[40:41], v[58:59]
	s_waitcnt lgkmcnt(0)
	s_barrier
	ds_read_b128 v[88:91], v93
	global_load_dword v36, v[48:49], off offset:1024
	global_load_dword v38, v[54:55], off offset:1024
	global_load_dwordx4 v[16:19], v[52:53], off
	global_load_dwordx4 v[20:23], v[52:53], off offset:-16
	v_lshl_add_u64 v[52:53], v[52:53], 0, s[88:89]
	s_waitcnt lgkmcnt(0)
	global_store_dwordx4 v[44:45], v[88:91], off
	s_waitcnt vmcnt(13)
	v_pk_mul_f32 v[160:161], v[136:137], v[144:145] op_sel_hi:[1,0]
	v_cvt_pk_bf16_f32 v162, v160, v161
	v_pk_fma_f32 v[2:3], v[136:137], v[146:147], v[2:3] op_sel_hi:[1,0,1]
	v_lshlrev_b32_e32 v164, 16, v162
	v_and_b32_e32 v165, 0xffff0000, v162
	v_lshrrev_b32_e32 v163, 16, v162
	ds_write_b16 v92, v162 offset:9472
	ds_write_b16 v92, v163 offset:9616
	v_pk_add_f32 v[50:51], v[50:51], v[164:165]
	v_pk_mul_f32 v[166:167], v[138:139], v[144:145] op_sel_hi:[1,0]
	v_cvt_pk_bf16_f32 v134, v166, v167
	v_pk_fma_f32 v[24:25], v[138:139], v[146:147], v[24:25] op_sel_hi:[1,0,1]
	v_lshlrev_b32_e32 v58, 16, v134
	v_and_b32_e32 v59, 0xffff0000, v134
	v_lshrrev_b32_e32 v135, 16, v134
	ds_write_b16 v92, v134 offset:9760
	ds_write_b16 v92, v135 offset:9904
	v_pk_add_f32 v[46:47], v[46:47], v[58:59]
	v_pk_mul_f32 v[160:161], v[140:141], v[144:145] op_sel_hi:[1,0]
	v_cvt_pk_bf16_f32 v162, v160, v161
	v_pk_fma_f32 v[26:27], v[140:141], v[146:147], v[26:27] op_sel_hi:[1,0,1]
	v_lshlrev_b32_e32 v164, 16, v162
	v_and_b32_e32 v165, 0xffff0000, v162
	v_lshrrev_b32_e32 v163, 16, v162
	ds_write_b16 v92, v162 offset:10048
	ds_write_b16 v92, v163 offset:10192
	v_pk_add_f32 v[42:43], v[42:43], v[164:165]
	v_pk_mul_f32 v[166:167], v[142:143], v[144:145] op_sel_hi:[1,0]
	v_cvt_pk_bf16_f32 v134, v166, v167
	v_pk_fma_f32 v[28:29], v[142:143], v[146:147], v[28:29] op_sel_hi:[1,0,1]
	v_lshlrev_b32_e32 v58, 16, v134
	v_and_b32_e32 v59, 0xffff0000, v134
	v_lshrrev_b32_e32 v135, 16, v134
	ds_write_b16 v92, v134 offset:10336
	ds_write_b16 v92, v135 offset:10480
	v_pk_add_f32 v[40:41], v[40:41], v[58:59]
	s_waitcnt lgkmcnt(0)
	s_barrier
; #define LAS __attribute__((address_space(3)))
; __device__ __forceinline__ bf16_t f2bf(float f) { return (bf16_t)(cvt_pk_bf16(f, 0.f) & 0xffffu); }
; __device__ __forceinline__ float bf2f(bf16_t b) { return __uint_as_float(((unsigned)b) << 16); }
; #define LBAR() do { asm volatile("s_waitcnt lgkmcnt(0)" ::: "memory"); __builtin_amdgcn_s_barrier(); asm volatile("" ::: "memory"); } while (0)
; __device__ void conv_unit(LAS unsigned char* lds, const float* src, int ld, int sn0, int nvalid, int k0, int krows,
;                           bf16_t* dst, int dn0, int Kdst, int kd0, const float* gs, const float* bs, float* c1, float* c2) {
;     ...
;     { const int k = k0 + kl; gn = gs ? gs[k] : 1.f; bn = bs ? bs[k] : 0.f;
; #pragma unroll
;       for (int j = 0; j < 8; ++j) wn[j] = (ng + j < nvalid) ? src[(size_t)k * ld + sn0 + ng + j] : 0.f; }
;     for (int kt = 0; kt < nkt; ++kt) {
;         float w[8]; const float g = gn, b = bn;
; #pragma unroll
;         for (int j = 0; j < 8; ++j) w[j] = wn[j];
;         if (kt + 1 < nkt) { const int k = k0 + (kt + 1) * 64 + kl; gn = gs ? gs[k] : 1.f; bn = bs ? bs[k] : 0.f;
; #pragma unroll
;             for (int j = 0; j < 8; ++j) wn[j] = (ng + j < nvalid) ? src[(size_t)k * ld + sn0 + ng + j] : 0.f; }
; #pragma unroll
;         for (int j = 0; j < 8; ++j) { const bf16_t wb = f2bf(w[j] * g); a1[j] += bf2f(wb); a2[j] += b * w[j]; T[(ng + j) * 72 + kl] = wb; }
;         LBAR();
;         { const int n = tid >> 3, ks = (tid & 7) * 8; const u32x4 v = *(const LAS u32x4*)(T + n * 72 + ks);
;           *(u32x4*)(dst + (size_t)(dn0 + n) * Kdst + kd0 + kt * 64 + ks) = v; }
;         LBAR();
;     }
	ds_read_b128 v[184:187], v93 offset:9472
	global_load_dword v144, v[48:49], off offset:1280
	global_load_dword v146, v[54:55], off offset:1280
	global_load_dwordx4 v[140:143], v[52:53], off
	global_load_dwordx4 v[136:139], v[52:53], off offset:-16
	v_lshl_add_u64 v[52:53], v[52:53], 0, s[88:89]
	s_waitcnt lgkmcnt(0)
	global_store_dwordx4 v[44:45], v[184:187], off offset:128
	s_waitcnt vmcnt(14)
	v_pk_mul_f32 v[160:161], v[148:149], v[156:157] op_sel_hi:[1,0]
	v_cvt_pk_bf16_f32 v162, v160, v161
	v_pk_fma_f32 v[2:3], v[148:149], v[158:159], v[2:3] op_sel_hi:[1,0,1]
	v_lshlrev_b32_e32 v164, 16, v162
	v_and_b32_e32 v165, 0xffff0000, v162
	v_lshrrev_b32_e32 v163, 16, v162
	ds_write_b16 v92, v162
	ds_write_b16 v92, v163 offset:144
	v_pk_add_f32 v[50:51], v[50:51], v[164:165]
	v_pk_mul_f32 v[166:167], v[150:151], v[156:157] op_sel_hi:[1,0]
	v_cvt_pk_bf16_f32 v134, v166, v167
	v_pk_fma_f32 v[24:25], v[150:151], v[158:159], v[24:25] op_sel_hi:[1,0,1]
	v_lshlrev_b32_e32 v58, 16, v134
	v_and_b32_e32 v59, 0xffff0000, v134
	v_lshrrev_b32_e32 v135, 16, v134
	ds_write_b16 v92, v134 offset:288
	ds_write_b16 v92, v135 offset:432
	v_pk_add_f32 v[46:47], v[46:47], v[58:59]
	v_pk_mul_f32 v[160:161], v[152:153], v[156:157] op_sel_hi:[1,0]
	v_cvt_pk_bf16_f32 v162, v160, v161
	v_pk_fma_f32 v[26:27], v[152:153], v[158:159], v[26:27] op_sel_hi:[1,0,1]
	v_lshlrev_b32_e32 v164, 16, v162
	v_and_b32_e32 v165, 0xffff0000, v162
	v_lshrrev_b32_e32 v163, 16, v162
	ds_write_b16 v92, v162 offset:576
	ds_write_b16 v92, v163 offset:720
	v_pk_add_f32 v[42:43], v[42:43], v[164:165]
	v_pk_mul_f32 v[166:167], v[154:155], v[156:157] op_sel_hi:[1,0]
	v_cvt_pk_bf16_f32 v134, v166, v167
	v_pk_fma_f32 v[28:29], v[154:155], v[158:159], v[28:29] op_sel_hi:[1,0,1]
	v_lshlrev_b32_e32 v58, 16, v134
	v_and_b32_e32 v59, 0xffff0000, v134
	v_lshrrev_b32_e32 v135, 16, v134
	ds_write_b16 v92, v134 offset:864
	ds_write_b16 v92, v135 offset:1008
	v_pk_add_f32 v[40:41], v[40:41], v[58:59]
	s_waitcnt lgkmcnt(0)
	s_barrier
	ds_read_b128 v[88:91], v93
	global_load_dword v156, v[48:49], off offset:1536
	global_load_dword v158, v[54:55], off offset:1536
	global_load_dwordx4 v[152:155], v[52:53], off
	global_load_dwordx4 v[148:151], v[52:53], off offset:-16
	v_lshl_add_u64 v[52:53], v[52:53], 0, s[88:89]
	s_waitcnt lgkmcnt(0)
	global_store_dwordx4 v[44:45], v[88:91], off offset:256
	s_waitcnt vmcnt(15)
	v_pk_mul_f32 v[160:161], v[12:13], v[56:57] op_sel_hi:[1,0]
	v_cvt_pk_bf16_f32 v162, v160, v161
	v_pk_fma_f32 v[2:3], v[12:13], v[30:31], v[2:3] op_sel_hi:[1,0,1]
	v_lshlrev_b32_e32 v164, 16, v162
	v_and_b32_e32 v165, 0xffff0000, v162
	v_lshrrev_b32_e32 v163, 16, v162
	ds_write_b16 v92, v162 offset:9472
	ds_write_b16 v92, v163 offset:9616
	v_pk_add_f32 v[50:51], v[50:51], v[164:165]
	v_pk_mul_f32 v[166:167], v[14:15], v[56:57] op_sel_hi:[1,0]
	v_cvt_pk_bf16_f32 v134, v166, v167
	v_pk_fma_f32 v[24:25], v[14:15], v[30:31], v[24:25] op_sel_hi:[1,0,1]
	v_lshlrev_b32_e32 v58, 16, v134
	v_and_b32_e32 v59, 0xffff0000, v134
	v_lshrrev_b32_e32 v135, 16, v134
	ds_write_b16 v92, v134 offset:9760
	ds_write_b16 v92, v135 offset:9904
	v_pk_add_f32 v[46:47], v[46:47], v[58:59]
	v_pk_mul_f32 v[160:161], v[8:9], v[56:57] op_sel_hi:[1,0]
	v_cvt_pk_bf16_f32 v162, v160, v161
	v_pk_fma_f32 v[26:27], v[8:9], v[30:31], v[26:27] op_sel_hi:[1,0,1]
	v_lshlrev_b32_e32 v164, 16, v162
	v_and_b32_e32 v165, 0xffff0000, v162
	v_lshrrev_b32_e32 v163, 16, v162
	ds_write_b16 v92, v162 offset:10048
	ds_write_b16 v92, v163 offset:10192
	v_pk_add_f32 v[42:43], v[42:43], v[164:165]
	v_pk_mul_f32 v[166:167], v[10:11], v[56:57] op_sel_hi:[1,0]
	v_cvt_pk_bf16_f32 v134, v166, v167
	v_pk_fma_f32 v[28:29], v[10:11], v[30:31], v[28:29] op_sel_hi:[1,0,1]
	v_lshlrev_b32_e32 v58, 16, v134
	v_and_b32_e32 v59, 0xffff0000, v134
	v_lshrrev_b32_e32 v135, 16, v134
	ds_write_b16 v92, v134 offset:10336
	ds_write_b16 v92, v135 offset:10480
	v_pk_add_f32 v[40:41], v[40:41], v[58:59]
	s_waitcnt lgkmcnt(0)
	s_barrier
	ds_read_b128 v[184:187], v93 offset:9472
	global_load_dword v56, v[48:49], off offset:1792
	global_load_dword v30, v[54:55], off offset:1792
	global_load_dwordx4 v[8:11], v[52:53], off
	global_load_dwordx4 v[12:15], v[52:53], off offset:-16
	v_lshl_add_u64 v[52:53], v[52:53], 0, s[88:89]
	s_waitcnt lgkmcnt(0)
	global_store_dwordx4 v[44:45], v[184:187], off offset:384
	s_waitcnt vmcnt(16)
	v_pk_mul_f32 v[160:161], v[20:21], v[36:37] op_sel_hi:[1,0]
	v_cvt_pk_bf16_f32 v162, v160, v161
	v_pk_fma_f32 v[2:3], v[20:21], v[38:39], v[2:3] op_sel_hi:[1,0,1]
	v_lshlrev_b32_e32 v164, 16, v162
	v_and_b32_e32 v165, 0xffff0000, v162
	v_lshrrev_b32_e32 v163, 16, v162
	ds_write_b16 v92, v162
	ds_write_b16 v92, v163 offset:144
	v_pk_add_f32 v[50:51], v[50:51], v[164:165]
	v_pk_mul_f32 v[166:167], v[22:23], v[36:37] op_sel_hi:[1,0]
	v_cvt_pk_bf16_f32 v134, v166, v167
	v_pk_fma_f32 v[24:25], v[22:23], v[38:39], v[24:25] op_sel_hi:[1,0,1]
	v_lshlrev_b32_e32 v58, 16, v134
	v_and_b32_e32 v59, 0xffff0000, v134
	v_lshrrev_b32_e32 v135, 16, v134
	ds_write_b16 v92, v134 offset:288
	ds_write_b16 v92, v135 offset:432
	v_pk_add_f32 v[46:47], v[46:47], v[58:59]
	v_pk_mul_f32 v[160:161], v[16:17], v[36:37] op_sel_hi:[1,0]
	v_cvt_pk_bf16_f32 v162, v160, v161
	v_pk_fma_f32 v[26:27], v[16:17], v[38:39], v[26:27] op_sel_hi:[1,0,1]
	v_lshlrev_b32_e32 v164, 16, v162
	v_and_b32_e32 v165, 0xffff0000, v162
	v_lshrrev_b32_e32 v163, 16, v162
	ds_write_b16 v92, v162 offset:576
	ds_write_b16 v92, v163 offset:720
	v_pk_add_f32 v[42:43], v[42:43], v[164:165]
	v_pk_mul_f32 v[166:167], v[18:19], v[36:37] op_sel_hi:[1,0]
	v_cvt_pk_bf16_f32 v134, v166, v167
	v_pk_fma_f32 v[28:29], v[18:19], v[38:39], v[28:29] op_sel_hi:[1,0,1]
	v_lshlrev_b32_e32 v58, 16, v134
	v_and_b32_e32 v59, 0xffff0000, v134
	v_lshrrev_b32_e32 v135, 16, v134
	ds_write_b16 v92, v134 offset:864
	ds_write_b16 v92, v135 offset:1008
	v_pk_add_f32 v[40:41], v[40:41], v[58:59]
	s_waitcnt lgkmcnt(0)
	s_barrier
; #define LAS __attribute__((address_space(3)))
; __device__ __forceinline__ bf16_t f2bf(float f) { return (bf16_t)(cvt_pk_bf16(f, 0.f) & 0xffffu); }
; __device__ __forceinline__ float bf2f(bf16_t b) { return __uint_as_float(((unsigned)b) << 16); }
; #define LBAR() do { asm volatile("s_waitcnt lgkmcnt(0)" ::: "memory"); __builtin_amdgcn_s_barrier(); asm volatile("" ::: "memory"); } while (0)
; __device__ void conv_unit(LAS unsigned char* lds, const float* src, int ld, int sn0, int nvalid, int k0, int krows,
;                           bf16_t* dst, int dn0, int Kdst, int kd0, const float* gs, const float* bs, float* c1, float* c2) {
;     ...
;     { const int k = k0 + kl; gn = gs ? gs[k] : 1.f; bn = bs ? bs[k] : 0.f;
; #pragma unroll
;       for (int j = 0; j < 8; ++j) wn[j] = (ng + j < nvalid) ? src[(size_t)k * ld + sn0 + ng + j] : 0.f; }
;     for (int kt = 0; kt < nkt; ++kt) {
;         float w[8]; const float g = gn, b = bn;
; #pragma unroll
;         for (int j = 0; j < 8; ++j) w[j] = wn[j];
;         if (kt + 1 < nkt) { const int k = k0 + (kt + 1) * 64 + kl; gn = gs ? gs[k] : 1.f; bn = bs ? bs[k] : 0.f;
; #pragma unroll
;             for (int j = 0; j < 8; ++j) wn[j] = (ng + j < nvalid) ? src[(size_t)k * ld + sn0 + ng + j] : 0.f; }
; #pragma unroll
;         for (int j = 0; j < 8; ++j) { const bf16_t wb = f2bf(w[j] * g); a1[j] += bf2f(wb); a2[j] += b * w[j]; T[(ng + j) * 72 + kl] = wb; }
;         LBAR();
;         { const int n = tid >> 3, ks = (tid & 7) * 8; const u32x4 v = *(const LAS u32x4*)(T + n * 72 + ks);
;           *(u32x4*)(dst + (size_t)(dn0 + n) * Kdst + kd0 + kt * 64 + ks) = v; }
;         LBAR();
;     }
	ds_read_b128 v[88:91], v93
	global_load_dword v36, v[48:49], off offset:2048
	global_load_dword v38, v[54:55], off offset:2048
	global_load_dwordx4 v[16:19], v[52:53], off
	global_load_dwordx4 v[20:23], v[52:53], off offset:-16
	v_lshl_add_u64 v[52:53], v[52:53], 0, s[88:89]
	s_waitcnt lgkmcnt(0)
	global_store_dwordx4 v[44:45], v[88:91], off offset:512
	s_waitcnt vmcnt(16)
	v_pk_mul_f32 v[160:161], v[136:137], v[144:145] op_sel_hi:[1,0]
	v_cvt_pk_bf16_f32 v162, v160, v161
	v_pk_fma_f32 v[2:3], v[136:137], v[146:147], v[2:3] op_sel_hi:[1,0,1]
	v_lshlrev_b32_e32 v164, 16, v162
	v_and_b32_e32 v165, 0xffff0000, v162
	v_lshrrev_b32_e32 v163, 16, v162
	ds_write_b16 v92, v162 offset:9472
	ds_write_b16 v92, v163 offset:9616
	v_pk_add_f32 v[50:51], v[50:51], v[164:165]
	v_pk_mul_f32 v[166:167], v[138:139], v[144:145] op_sel_hi:[1,0]
	v_cvt_pk_bf16_f32 v134, v166, v167
	v_pk_fma_f32 v[24:25], v[138:139], v[146:147], v[24:25] op_sel_hi:[1,0,1]
	v_lshlrev_b32_e32 v58, 16, v134
	v_and_b32_e32 v59, 0xffff0000, v134
	v_lshrrev_b32_e32 v135, 16, v134
	ds_write_b16 v92, v134 offset:9760
	ds_write_b16 v92, v135 offset:9904
	v_pk_add_f32 v[46:47], v[46:47], v[58:59]
	v_pk_mul_f32 v[160:161], v[140:141], v[144:145] op_sel_hi:[1,0]
	v_cvt_pk_bf16_f32 v162, v160, v161
	v_pk_fma_f32 v[26:27], v[140:141], v[146:147], v[26:27] op_sel_hi:[1,0,1]
	v_lshlrev_b32_e32 v164, 16, v162
	v_and_b32_e32 v165, 0xffff0000, v162
	v_lshrrev_b32_e32 v163, 16, v162
	ds_write_b16 v92, v162 offset:10048
	ds_write_b16 v92, v163 offset:10192
	v_pk_add_f32 v[42:43], v[42:43], v[164:165]
	v_pk_mul_f32 v[166:167], v[142:143], v[144:145] op_sel_hi:[1,0]
	v_cvt_pk_bf16_f32 v134, v166, v167
	v_pk_fma_f32 v[28:29], v[142:143], v[146:147], v[28:29] op_sel_hi:[1,0,1]
	v_lshlrev_b32_e32 v58, 16, v134
	v_and_b32_e32 v59, 0xffff0000, v134
	v_lshrrev_b32_e32 v135, 16, v134
	ds_write_b16 v92, v134 offset:10336
	ds_write_b16 v92, v135 offset:10480
	v_pk_add_f32 v[40:41], v[40:41], v[58:59]
	s_waitcnt lgkmcnt(0)
	s_barrier
	ds_read_b128 v[184:187], v93 offset:9472
	global_load_dword v144, v[48:49], off offset:2304
	global_load_dword v146, v[54:55], off offset:2304
	global_load_dwordx4 v[140:143], v[52:53], off
	global_load_dwordx4 v[136:139], v[52:53], off offset:-16
	v_lshl_add_u64 v[52:53], v[52:53], 0, s[88:89]
	s_waitcnt lgkmcnt(0)
	global_store_dwordx4 v[44:45], v[184:187], off offset:640
	s_waitcnt vmcnt(16)
	v_pk_mul_f32 v[160:161], v[148:149], v[156:157] op_sel_hi:[1,0]
	v_cvt_pk_bf16_f32 v162, v160, v161
	v_pk_fma_f32 v[2:3], v[148:149], v[158:159], v[2:3] op_sel_hi:[1,0,1]
	v_lshlrev_b32_e32 v164, 16, v162
	v_and_b32_e32 v165, 0xffff0000, v162
	v_lshrrev_b32_e32 v163, 16, v162
	ds_write_b16 v92, v162
	ds_write_b16 v92, v163 offset:144
	v_pk_add_f32 v[50:51], v[50:51], v[164:165]
	v_pk_mul_f32 v[166:167], v[150:151], v[156:157] op_sel_hi:[1,0]
	v_cvt_pk_bf16_f32 v134, v166, v167
	v_pk_fma_f32 v[24:25], v[150:151], v[158:159], v[24:25] op_sel_hi:[1,0,1]
	v_lshlrev_b32_e32 v58, 16, v134
	v_and_b32_e32 v59, 0xffff0000, v134
	v_lshrrev_b32_e32 v135, 16, v134
	ds_write_b16 v92, v134 offset:288
	ds_write_b16 v92, v135 offset:432
	v_pk_add_f32 v[46:47], v[46:47], v[58:59]
	v_pk_mul_f32 v[160:161], v[152:153], v[156:157] op_sel_hi:[1,0]
	v_cvt_pk_bf16_f32 v162, v160, v161
	v_pk_fma_f32 v[26:27], v[152:153], v[158:159], v[26:27] op_sel_hi:[1,0,1]
	v_lshlrev_b32_e32 v164, 16, v162
	v_and_b32_e32 v165, 0xffff0000, v162
	v_lshrrev_b32_e32 v163, 16, v162
	ds_write_b16 v92, v162 offset:576
	ds_write_b16 v92, v163 offset:720
	v_pk_add_f32 v[42:43], v[42:43], v[164:165]
	v_pk_mul_f32 v[166:167], v[154:155], v[156:157] op_sel_hi:[1,0]
	v_cvt_pk_bf16_f32 v134, v166, v167
	v_pk_fma_f32 v[28:29], v[154:155], v[158:159], v[28:29] op_sel_hi:[1,0,1]
	v_lshlrev_b32_e32 v58, 16, v134
	v_and_b32_e32 v59, 0xffff0000, v134
	v_lshrrev_b32_e32 v135, 16, v134
	ds_write_b16 v92, v134 offset:864
	ds_write_b16 v92, v135 offset:1008
	v_pk_add_f32 v[40:41], v[40:41], v[58:59]
	s_waitcnt lgkmcnt(0)
	s_barrier
	ds_read_b128 v[88:91], v93
	global_load_dword v156, v[48:49], off offset:2560
	global_load_dword v158, v[54:55], off offset:2560
	global_load_dwordx4 v[152:155], v[52:53], off
	global_load_dwordx4 v[148:151], v[52:53], off offset:-16
	v_lshl_add_u64 v[52:53], v[52:53], 0, s[88:89]
	s_waitcnt lgkmcnt(0)
	global_store_dwordx4 v[44:45], v[88:91], off offset:768
	s_waitcnt vmcnt(16)
	v_pk_mul_f32 v[160:161], v[12:13], v[56:57] op_sel_hi:[1,0]
	v_cvt_pk_bf16_f32 v162, v160, v161
	v_pk_fma_f32 v[2:3], v[12:13], v[30:31], v[2:3] op_sel_hi:[1,0,1]
	v_lshlrev_b32_e32 v164, 16, v162
	v_and_b32_e32 v165, 0xffff0000, v162
	v_lshrrev_b32_e32 v163, 16, v162
	ds_write_b16 v92, v162 offset:9472
	ds_write_b16 v92, v163 offset:9616
	v_pk_add_f32 v[50:51], v[50:51], v[164:165]
	v_pk_mul_f32 v[166:167], v[14:15], v[56:57] op_sel_hi:[1,0]
	v_cvt_pk_bf16_f32 v134, v166, v167
	v_pk_fma_f32 v[24:25], v[14:15], v[30:31], v[24:25] op_sel_hi:[1,0,1]
	v_lshlrev_b32_e32 v58, 16, v134
	v_and_b32_e32 v59, 0xffff0000, v134
	v_lshrrev_b32_e32 v135, 16, v134
	ds_write_b16 v92, v134 offset:9760
	ds_write_b16 v92, v135 offset:9904
	v_pk_add_f32 v[46:47], v[46:47], v[58:59]
	v_pk_mul_f32 v[160:161], v[8:9], v[56:57] op_sel_hi:[1,0]
	v_cvt_pk_bf16_f32 v162, v160, v161
	v_pk_fma_f32 v[26:27], v[8:9], v[30:31], v[26:27] op_sel_hi:[1,0,1]
	v_lshlrev_b32_e32 v164, 16, v162
	v_and_b32_e32 v165, 0xffff0000, v162
	v_lshrrev_b32_e32 v163, 16, v162
	ds_write_b16 v92, v162 offset:10048
	ds_write_b16 v92, v163 offset:10192
	v_pk_add_f32 v[42:43], v[42:43], v[164:165]
	v_pk_mul_f32 v[166:167], v[10:11], v[56:57] op_sel_hi:[1,0]
	v_cvt_pk_bf16_f32 v134, v166, v167
	v_pk_fma_f32 v[28:29], v[10:11], v[30:31], v[28:29] op_sel_hi:[1,0,1]
	v_lshlrev_b32_e32 v58, 16, v134
	v_and_b32_e32 v59, 0xffff0000, v134
	v_lshrrev_b32_e32 v135, 16, v134
	ds_write_b16 v92, v134 offset:10336
	ds_write_b16 v92, v135 offset:10480
	v_pk_add_f32 v[40:41], v[40:41], v[58:59]
	s_waitcnt lgkmcnt(0)
	s_barrier
; #define LAS __attribute__((address_space(3)))
; __device__ __forceinline__ bf16_t f2bf(float f) { return (bf16_t)(cvt_pk_bf16(f, 0.f) & 0xffffu); }
; __device__ __forceinline__ float bf2f(bf16_t b) { return __uint_as_float(((unsigned)b) << 16); }
; #define LBAR() do { asm volatile("s_waitcnt lgkmcnt(0)" ::: "memory"); __builtin_amdgcn_s_barrier(); asm volatile("" ::: "memory"); } while (0)
; __device__ void conv_unit(LAS unsigned char* lds, const float* src, int ld, int sn0, int nvalid, int k0, int krows,
;                           bf16_t* dst, int dn0, int Kdst, int kd0, const float* gs, const float* bs, float* c1, float* c2) {
;     ...
;     { const int k = k0 + kl; gn = gs ? gs[k] : 1.f; bn = bs ? bs[k] : 0.f;
; #pragma unroll
;       for (int j = 0; j < 8; ++j) wn[j] = (ng + j < nvalid) ? src[(size_t)k * ld + sn0 + ng + j] : 0.f; }
;     for (int kt = 0; kt < nkt; ++kt) {
;         float w[8]; const float g = gn, b = bn;
; #pragma unroll
;         for (int j = 0; j < 8; ++j) w[j] = wn[j];
;         if (kt + 1 < nkt) { const int k = k0 + (kt + 1) * 64 + kl; gn = gs ? gs[k] : 1.f; bn = bs ? bs[k] : 0.f;
; #pragma unroll
;             for (int j = 0; j < 8; ++j) wn[j] = (ng + j < nvalid) ? src[(size_t)k * ld + sn0 + ng + j] : 0.f; }
; #pragma unroll
;         for (int j = 0; j < 8; ++j) { const bf16_t wb = f2bf(w[j] * g); a1[j] += bf2f(wb); a2[j] += b * w[j]; T[(ng + j) * 72 + kl] = wb; }
;         LBAR();
;         { const int n = tid >> 3, ks = (tid & 7) * 8; const u32x4 v = *(const LAS u32x4*)(T + n * 72 + ks);
;           *(u32x4*)(dst + (size_t)(dn0 + n) * Kdst + kd0 + kt * 64 + ks) = v; }
;         LBAR();
;     }
	ds_read_b128 v[184:187], v93 offset:9472
	global_load_dword v56, v[48:49], off offset:2816
	global_load_dword v30, v[54:55], off offset:2816
	global_load_dwordx4 v[8:11], v[52:53], off
	global_load_dwordx4 v[12:15], v[52:53], off offset:-16
	v_lshl_add_u64 v[52:53], v[52:53], 0, s[88:89]
	s_waitcnt lgkmcnt(0)
	global_store_dwordx4 v[44:45], v[184:187], off offset:896
	s_waitcnt vmcnt(16)
	v_pk_mul_f32 v[160:161], v[20:21], v[36:37] op_sel_hi:[1,0]
	v_cvt_pk_bf16_f32 v162, v160, v161
	v_pk_fma_f32 v[2:3], v[20:21], v[38:39], v[2:3] op_sel_hi:[1,0,1]
	v_lshlrev_b32_e32 v164, 16, v162
	v_and_b32_e32 v165, 0xffff0000, v162
	v_lshrrev_b32_e32 v163, 16, v162
	ds_write_b16 v92, v162
	ds_write_b16 v92, v163 offset:144
	v_pk_add_f32 v[50:51], v[50:51], v[164:165]
	v_pk_mul_f32 v[166:167], v[22:23], v[36:37] op_sel_hi:[1,0]
	v_cvt_pk_bf16_f32 v134, v166, v167
	v_pk_fma_f32 v[24:25], v[22:23], v[38:39], v[24:25] op_sel_hi:[1,0,1]
	v_lshlrev_b32_e32 v58, 16, v134
	v_and_b32_e32 v59, 0xffff0000, v134
	v_lshrrev_b32_e32 v135, 16, v134
	ds_write_b16 v92, v134 offset:288
	ds_write_b16 v92, v135 offset:432
	v_pk_add_f32 v[46:47], v[46:47], v[58:59]
	v_pk_mul_f32 v[160:161], v[16:17], v[36:37] op_sel_hi:[1,0]
	v_cvt_pk_bf16_f32 v162, v160, v161
	v_pk_fma_f32 v[26:27], v[16:17], v[38:39], v[26:27] op_sel_hi:[1,0,1]
	v_lshlrev_b32_e32 v164, 16, v162
	v_and_b32_e32 v165, 0xffff0000, v162
	v_lshrrev_b32_e32 v163, 16, v162
	ds_write_b16 v92, v162 offset:576
	ds_write_b16 v92, v163 offset:720
	v_pk_add_f32 v[42:43], v[42:43], v[164:165]
	v_pk_mul_f32 v[166:167], v[18:19], v[36:37] op_sel_hi:[1,0]
	v_cvt_pk_bf16_f32 v134, v166, v167
	v_pk_fma_f32 v[28:29], v[18:19], v[38:39], v[28:29] op_sel_hi:[1,0,1]
	v_lshlrev_b32_e32 v58, 16, v134
	v_and_b32_e32 v59, 0xffff0000, v134
	v_lshrrev_b32_e32 v135, 16, v134
	ds_write_b16 v92, v134 offset:864
	ds_write_b16 v92, v135 offset:1008
	v_pk_add_f32 v[40:41], v[40:41], v[58:59]
	s_waitcnt lgkmcnt(0)
	s_barrier
	ds_read_b128 v[88:91], v93
	global_load_dword v36, v[48:49], off offset:3072
	global_load_dword v38, v[54:55], off offset:3072
	global_load_dwordx4 v[16:19], v[52:53], off
	global_load_dwordx4 v[20:23], v[52:53], off offset:-16
	v_lshl_add_u64 v[52:53], v[52:53], 0, s[88:89]
	s_waitcnt lgkmcnt(0)
	global_store_dwordx4 v[44:45], v[88:91], off offset:1024
	s_waitcnt vmcnt(16)
	v_pk_mul_f32 v[160:161], v[136:137], v[144:145] op_sel_hi:[1,0]
	v_cvt_pk_bf16_f32 v162, v160, v161
	v_pk_fma_f32 v[2:3], v[136:137], v[146:147], v[2:3] op_sel_hi:[1,0,1]
	v_lshlrev_b32_e32 v164, 16, v162
	v_and_b32_e32 v165, 0xffff0000, v162
	v_lshrrev_b32_e32 v163, 16, v162
	ds_write_b16 v92, v162 offset:9472
	ds_write_b16 v92, v163 offset:9616
	v_pk_add_f32 v[50:51], v[50:51], v[164:165]
	v_pk_mul_f32 v[166:167], v[138:139], v[144:145] op_sel_hi:[1,0]
	v_cvt_pk_bf16_f32 v134, v166, v167
	v_pk_fma_f32 v[24:25], v[138:139], v[146:147], v[24:25] op_sel_hi:[1,0,1]
	v_lshlrev_b32_e32 v58, 16, v134
	v_and_b32_e32 v59, 0xffff0000, v134
	v_lshrrev_b32_e32 v135, 16, v134
	ds_write_b16 v92, v134 offset:9760
	ds_write_b16 v92, v135 offset:9904
	v_pk_add_f32 v[46:47], v[46:47], v[58:59]
	v_pk_mul_f32 v[160:161], v[140:141], v[144:145] op_sel_hi:[1,0]
	v_cvt_pk_bf16_f32 v162, v160, v161
	v_pk_fma_f32 v[26:27], v[140:141], v[146:147], v[26:27] op_sel_hi:[1,0,1]
	v_lshlrev_b32_e32 v164, 16, v162
	v_and_b32_e32 v165, 0xffff0000, v162
	v_lshrrev_b32_e32 v163, 16, v162
	ds_write_b16 v92, v162 offset:10048
	ds_write_b16 v92, v163 offset:10192
	v_pk_add_f32 v[42:43], v[42:43], v[164:165]
	v_pk_mul_f32 v[166:167], v[142:143], v[144:145] op_sel_hi:[1,0]
	v_cvt_pk_bf16_f32 v134, v166, v167
	v_pk_fma_f32 v[28:29], v[142:143], v[146:147], v[28:29] op_sel_hi:[1,0,1]
	v_lshlrev_b32_e32 v58, 16, v134
	v_and_b32_e32 v59, 0xffff0000, v134
	v_lshrrev_b32_e32 v135, 16, v134
	ds_write_b16 v92, v134 offset:10336
	ds_write_b16 v92, v135 offset:10480
	v_pk_add_f32 v[40:41], v[40:41], v[58:59]
	s_waitcnt lgkmcnt(0)
	s_barrier
	ds_read_b128 v[184:187], v93 offset:9472
	global_load_dword v144, v[48:49], off offset:3328
	global_load_dword v146, v[54:55], off offset:3328
	global_load_dwordx4 v[140:143], v[52:53], off
	global_load_dwordx4 v[136:139], v[52:53], off offset:-16
	v_lshl_add_u64 v[52:53], v[52:53], 0, s[88:89]
	s_waitcnt lgkmcnt(0)
	global_store_dwordx4 v[44:45], v[184:187], off offset:1152
	s_waitcnt vmcnt(16)
	v_pk_mul_f32 v[160:161], v[148:149], v[156:157] op_sel_hi:[1,0]
	v_cvt_pk_bf16_f32 v162, v160, v161
	v_pk_fma_f32 v[2:3], v[148:149], v[158:159], v[2:3] op_sel_hi:[1,0,1]
	v_lshlrev_b32_e32 v164, 16, v162
	v_and_b32_e32 v165, 0xffff0000, v162
	v_lshrrev_b32_e32 v163, 16, v162
	ds_write_b16 v92, v162
	ds_write_b16 v92, v163 offset:144
	v_pk_add_f32 v[50:51], v[50:51], v[164:165]
	v_pk_mul_f32 v[166:167], v[150:151], v[156:157] op_sel_hi:[1,0]
	v_cvt_pk_bf16_f32 v134, v166, v167
	v_pk_fma_f32 v[24:25], v[150:151], v[158:159], v[24:25] op_sel_hi:[1,0,1]
	v_lshlrev_b32_e32 v58, 16, v134
	v_and_b32_e32 v59, 0xffff0000, v134
	v_lshrrev_b32_e32 v135, 16, v134
	ds_write_b16 v92, v134 offset:288
	ds_write_b16 v92, v135 offset:432
	v_pk_add_f32 v[46:47], v[46:47], v[58:59]
	v_pk_mul_f32 v[160:161], v[152:153], v[156:157] op_sel_hi:[1,0]
	v_cvt_pk_bf16_f32 v162, v160, v161
	v_pk_fma_f32 v[26:27], v[152:153], v[158:159], v[26:27] op_sel_hi:[1,0,1]
	v_lshlrev_b32_e32 v164, 16, v162
	v_and_b32_e32 v165, 0xffff0000, v162
	v_lshrrev_b32_e32 v163, 16, v162
	ds_write_b16 v92, v162 offset:576
	ds_write_b16 v92, v163 offset:720
	v_pk_add_f32 v[42:43], v[42:43], v[164:165]
	v_pk_mul_f32 v[166:167], v[154:155], v[156:157] op_sel_hi:[1,0]
	v_cvt_pk_bf16_f32 v134, v166, v167
	v_pk_fma_f32 v[28:29], v[154:155], v[158:159], v[28:29] op_sel_hi:[1,0,1]
	v_lshlrev_b32_e32 v58, 16, v134
	v_and_b32_e32 v59, 0xffff0000, v134
	v_lshrrev_b32_e32 v135, 16, v134
	ds_write_b16 v92, v134 offset:864
	ds_write_b16 v92, v135 offset:1008
	v_pk_add_f32 v[40:41], v[40:41], v[58:59]
	s_waitcnt lgkmcnt(0)
	s_barrier
; #define LAS __attribute__((address_space(3)))
; __device__ __forceinline__ bf16_t f2bf(float f) { return (bf16_t)(cvt_pk_bf16(f, 0.f) & 0xffffu); }
; __device__ __forceinline__ float bf2f(bf16_t b) { return __uint_as_float(((unsigned)b) << 16); }
; #define LBAR() do { asm volatile("s_waitcnt lgkmcnt(0)" ::: "memory"); __builtin_amdgcn_s_barrier(); asm volatile("" ::: "memory"); } while (0)
; __device__ void conv_unit(LAS unsigned char* lds, const float* src, int ld, int sn0, int nvalid, int k0, int krows,
;                           bf16_t* dst, int dn0, int Kdst, int kd0, const float* gs, const float* bs, float* c1, float* c2) {
;     ...
;     { const int k = k0 + kl; gn = gs ? gs[k] : 1.f; bn = bs ? bs[k] : 0.f;
; #pragma unroll
;       for (int j = 0; j < 8; ++j) wn[j] = (ng + j < nvalid) ? src[(size_t)k * ld + sn0 + ng + j] : 0.f; }
;     for (int kt = 0; kt < nkt; ++kt) {
;         float w[8]; const float g = gn, b = bn;
; #pragma unroll
;         for (int j = 0; j < 8; ++j) w[j] = wn[j];
;         if (kt + 1 < nkt) { const int k = k0 + (kt + 1) * 64 + kl; gn = gs ? gs[k] : 1.f; bn = bs ? bs[k] : 0.f;
; #pragma unroll
;             for (int j = 0; j < 8; ++j) wn[j] = (ng + j < nvalid) ? src[(size_t)k * ld + sn0 + ng + j] : 0.f; }
; #pragma unroll
;         for (int j = 0; j < 8; ++j) { const bf16_t wb = f2bf(w[j] * g); a1[j] += bf2f(wb); a2[j] += b * w[j]; T[(ng + j) * 72 + kl] = wb; }
;         LBAR();
;         { const int n = tid >> 3, ks = (tid & 7) * 8; const u32x4 v = *(const LAS u32x4*)(T + n * 72 + ks);
;           *(u32x4*)(dst + (size_t)(dn0 + n) * Kdst + kd0 + kt * 64 + ks) = v; }
;         LBAR();
;     }
	ds_read_b128 v[88:91], v93
	global_load_dword v156, v[48:49], off offset:3584
	global_load_dword v158, v[54:55], off offset:3584
	global_load_dwordx4 v[152:155], v[52:53], off
	global_load_dwordx4 v[148:151], v[52:53], off offset:-16
	v_lshl_add_u64 v[52:53], v[52:53], 0, s[88:89]
	s_waitcnt lgkmcnt(0)
	global_store_dwordx4 v[44:45], v[88:91], off offset:1280
	s_waitcnt vmcnt(16)
	v_pk_mul_f32 v[160:161], v[12:13], v[56:57] op_sel_hi:[1,0]
	v_cvt_pk_bf16_f32 v162, v160, v161
	v_pk_fma_f32 v[2:3], v[12:13], v[30:31], v[2:3] op_sel_hi:[1,0,1]
	v_lshlrev_b32_e32 v164, 16, v162
	v_and_b32_e32 v165, 0xffff0000, v162
	v_lshrrev_b32_e32 v163, 16, v162
	ds_write_b16 v92, v162 offset:9472
	ds_write_b16 v92, v163 offset:9616
	v_pk_add_f32 v[50:51], v[50:51], v[164:165]
	v_pk_mul_f32 v[166:167], v[14:15], v[56:57] op_sel_hi:[1,0]
	v_cvt_pk_bf16_f32 v134, v166, v167
	v_pk_fma_f32 v[24:25], v[14:15], v[30:31], v[24:25] op_sel_hi:[1,0,1]
	v_lshlrev_b32_e32 v58, 16, v134
	v_and_b32_e32 v59, 0xffff0000, v134
	v_lshrrev_b32_e32 v135, 16, v134
	ds_write_b16 v92, v134 offset:9760
	ds_write_b16 v92, v135 offset:9904
	v_pk_add_f32 v[46:47], v[46:47], v[58:59]
	v_pk_mul_f32 v[160:161], v[8:9], v[56:57] op_sel_hi:[1,0]
	v_cvt_pk_bf16_f32 v162, v160, v161
	v_pk_fma_f32 v[26:27], v[8:9], v[30:31], v[26:27] op_sel_hi:[1,0,1]
	v_lshlrev_b32_e32 v164, 16, v162
	v_and_b32_e32 v165, 0xffff0000, v162
	v_lshrrev_b32_e32 v163, 16, v162
	ds_write_b16 v92, v162 offset:10048
	ds_write_b16 v92, v163 offset:10192
	v_pk_add_f32 v[42:43], v[42:43], v[164:165]
	v_pk_mul_f32 v[166:167], v[10:11], v[56:57] op_sel_hi:[1,0]
	v_cvt_pk_bf16_f32 v134, v166, v167
	v_pk_fma_f32 v[28:29], v[10:11], v[30:31], v[28:29] op_sel_hi:[1,0,1]
	v_lshlrev_b32_e32 v58, 16, v134
	v_and_b32_e32 v59, 0xffff0000, v134
	v_lshrrev_b32_e32 v135, 16, v134
	ds_write_b16 v92, v134 offset:10336
	ds_write_b16 v92, v135 offset:10480
	v_pk_add_f32 v[40:41], v[40:41], v[58:59]
	s_waitcnt lgkmcnt(0)
	s_barrier
	ds_read_b128 v[184:187], v93 offset:9472
	global_load_dword v56, v[48:49], off offset:3840
	global_load_dword v30, v[54:55], off offset:3840
	global_load_dwordx4 v[8:11], v[52:53], off
	global_load_dwordx4 v[12:15], v[52:53], off offset:-16
	v_lshl_add_u64 v[52:53], v[52:53], 0, s[88:89]
	s_waitcnt lgkmcnt(0)
	global_store_dwordx4 v[44:45], v[184:187], off offset:1408
	s_waitcnt vmcnt(16)
	v_pk_mul_f32 v[160:161], v[20:21], v[36:37] op_sel_hi:[1,0]
	v_cvt_pk_bf16_f32 v162, v160, v161
	v_pk_fma_f32 v[2:3], v[20:21], v[38:39], v[2:3] op_sel_hi:[1,0,1]
	v_lshlrev_b32_e32 v164, 16, v162
	v_and_b32_e32 v165, 0xffff0000, v162
	v_lshrrev_b32_e32 v163, 16, v162
	ds_write_b16 v92, v162
	ds_write_b16 v92, v163 offset:144
	v_pk_add_f32 v[50:51], v[50:51], v[164:165]
	v_pk_mul_f32 v[166:167], v[22:23], v[36:37] op_sel_hi:[1,0]
	v_cvt_pk_bf16_f32 v134, v166, v167
	v_pk_fma_f32 v[24:25], v[22:23], v[38:39], v[24:25] op_sel_hi:[1,0,1]
	v_lshlrev_b32_e32 v58, 16, v134
	v_and_b32_e32 v59, 0xffff0000, v134
	v_lshrrev_b32_e32 v135, 16, v134
	ds_write_b16 v92, v134 offset:288
	ds_write_b16 v92, v135 offset:432
	v_pk_add_f32 v[46:47], v[46:47], v[58:59]
	v_pk_mul_f32 v[160:161], v[16:17], v[36:37] op_sel_hi:[1,0]
	v_cvt_pk_bf16_f32 v162, v160, v161
	v_pk_fma_f32 v[26:27], v[16:17], v[38:39], v[26:27] op_sel_hi:[1,0,1]
	v_lshlrev_b32_e32 v164, 16, v162
	v_and_b32_e32 v165, 0xffff0000, v162
	v_lshrrev_b32_e32 v163, 16, v162
	ds_write_b16 v92, v162 offset:576
	ds_write_b16 v92, v163 offset:720
	v_pk_add_f32 v[42:43], v[42:43], v[164:165]
	v_pk_mul_f32 v[166:167], v[18:19], v[36:37] op_sel_hi:[1,0]
	v_cvt_pk_bf16_f32 v134, v166, v167
	v_pk_fma_f32 v[28:29], v[18:19], v[38:39], v[28:29] op_sel_hi:[1,0,1]
	v_lshlrev_b32_e32 v58, 16, v134
	v_and_b32_e32 v59, 0xffff0000, v134
	v_lshrrev_b32_e32 v135, 16, v134
	ds_write_b16 v92, v134 offset:864
	ds_write_b16 v92, v135 offset:1008
	v_pk_add_f32 v[40:41], v[40:41], v[58:59]
	s_waitcnt lgkmcnt(0)
	s_barrier
	ds_read_b128 v[88:91], v93
	s_waitcnt lgkmcnt(0)
	global_store_dwordx4 v[44:45], v[88:91], off offset:1536
	s_waitcnt vmcnt(12)
	v_pk_mul_f32 v[160:161], v[136:137], v[144:145] op_sel_hi:[1,0]
	v_cvt_pk_bf16_f32 v162, v160, v161
	v_pk_fma_f32 v[2:3], v[136:137], v[146:147], v[2:3] op_sel_hi:[1,0,1]
	v_lshlrev_b32_e32 v164, 16, v162
	v_and_b32_e32 v165, 0xffff0000, v162
	v_lshrrev_b32_e32 v163, 16, v162
	ds_write_b16 v92, v162 offset:9472
	ds_write_b16 v92, v163 offset:9616
	v_pk_add_f32 v[50:51], v[50:51], v[164:165]
	v_pk_mul_f32 v[166:167], v[138:139], v[144:145] op_sel_hi:[1,0]
	v_cvt_pk_bf16_f32 v134, v166, v167
	v_pk_fma_f32 v[24:25], v[138:139], v[146:147], v[24:25] op_sel_hi:[1,0,1]
	v_lshlrev_b32_e32 v58, 16, v134
	v_and_b32_e32 v59, 0xffff0000, v134
	v_lshrrev_b32_e32 v135, 16, v134
	ds_write_b16 v92, v134 offset:9760
	ds_write_b16 v92, v135 offset:9904
	v_pk_add_f32 v[46:47], v[46:47], v[58:59]
	v_pk_mul_f32 v[160:161], v[140:141], v[144:145] op_sel_hi:[1,0]
	v_cvt_pk_bf16_f32 v162, v160, v161
	v_pk_fma_f32 v[26:27], v[140:141], v[146:147], v[26:27] op_sel_hi:[1,0,1]
	v_lshlrev_b32_e32 v164, 16, v162
	v_and_b32_e32 v165, 0xffff0000, v162
	v_lshrrev_b32_e32 v163, 16, v162
	ds_write_b16 v92, v162 offset:10048
	ds_write_b16 v92, v163 offset:10192
	v_pk_add_f32 v[42:43], v[42:43], v[164:165]
	v_pk_mul_f32 v[166:167], v[142:143], v[144:145] op_sel_hi:[1,0]
	v_cvt_pk_bf16_f32 v134, v166, v167
	v_pk_fma_f32 v[28:29], v[142:143], v[146:147], v[28:29] op_sel_hi:[1,0,1]
	v_lshlrev_b32_e32 v58, 16, v134
	v_and_b32_e32 v59, 0xffff0000, v134
	v_lshrrev_b32_e32 v135, 16, v134
	ds_write_b16 v92, v134 offset:10336
	ds_write_b16 v92, v135 offset:10480
	v_pk_add_f32 v[40:41], v[40:41], v[58:59]
	s_waitcnt lgkmcnt(0)
	s_barrier
; #define LAS __attribute__((address_space(3)))
; __device__ __forceinline__ bf16_t f2bf(float f) { return (bf16_t)(cvt_pk_bf16(f, 0.f) & 0xffffu); }
; __device__ __forceinline__ float bf2f(bf16_t b) { return __uint_as_float(((unsigned)b) << 16); }
; #define LBAR() do { asm volatile("s_waitcnt lgkmcnt(0)" ::: "memory"); __builtin_amdgcn_s_barrier(); asm volatile("" ::: "memory"); } while (0)
; __device__ void conv_unit(LAS unsigned char* lds, const float* src, int ld, int sn0, int nvalid, int k0, int krows,
;                           bf16_t* dst, int dn0, int Kdst, int kd0, const float* gs, const float* bs, float* c1, float* c2) {
;     ...
;     for (int kt = 0; kt < nkt; ++kt) {
;         float w[8]; const float g = gn, b = bn;
; #pragma unroll
;         for (int j = 0; j < 8; ++j) w[j] = wn[j];
;         if (kt + 1 < nkt) { const int k = k0 + (kt + 1) * 64 + kl; gn = gs ? gs[k] : 1.f; bn = bs ? bs[k] : 0.f;
; #pragma unroll
;             for (int j = 0; j < 8; ++j) wn[j] = (ng + j < nvalid) ? src[(size_t)k * ld + sn0 + ng + j] : 0.f; }
; #pragma unroll
;         for (int j = 0; j < 8; ++j) { const bf16_t wb = f2bf(w[j] * g); a1[j] += bf2f(wb); a2[j] += b * w[j]; T[(ng + j) * 72 + kl] = wb; }
;         LBAR();
;         { const int n = tid >> 3, ks = (tid & 7) * 8; const u32x4 v = *(const LAS u32x4*)(T + n * 72 + ks);
;           *(u32x4*)(dst + (size_t)(dn0 + n) * Kdst + kd0 + kt * 64 + ks) = v; }
;         LBAR();
;     }
;     if (c1) {
; #pragma unroll
;         for (int j = 0; j < 8; ++j) red[kl * 65 + ng + j] = a1[j];
;         LBAR();
;         if (tid < 64) { float sm = 0.f; for (int q = 0; q < 64; ++q) sm += red[q * 65 + tid]; c1[dn0 + tid] = sm; }
;         LBAR();
	ds_read_b128 v[184:187], v93 offset:9472
	s_waitcnt lgkmcnt(0)
	global_store_dwordx4 v[44:45], v[184:187], off offset:1664
	s_waitcnt vmcnt(8)
	v_pk_mul_f32 v[160:161], v[148:149], v[156:157] op_sel_hi:[1,0]
	v_cvt_pk_bf16_f32 v162, v160, v161
	v_pk_fma_f32 v[2:3], v[148:149], v[158:159], v[2:3] op_sel_hi:[1,0,1]
	v_lshlrev_b32_e32 v164, 16, v162
	v_and_b32_e32 v165, 0xffff0000, v162
	v_lshrrev_b32_e32 v163, 16, v162
	ds_write_b16 v92, v162
	ds_write_b16 v92, v163 offset:144
	v_pk_add_f32 v[50:51], v[50:51], v[164:165]
	v_pk_mul_f32 v[166:167], v[150:151], v[156:157] op_sel_hi:[1,0]
	v_cvt_pk_bf16_f32 v134, v166, v167
	v_pk_fma_f32 v[24:25], v[150:151], v[158:159], v[24:25] op_sel_hi:[1,0,1]
	v_lshlrev_b32_e32 v58, 16, v134
	v_and_b32_e32 v59, 0xffff0000, v134
	v_lshrrev_b32_e32 v135, 16, v134
	ds_write_b16 v92, v134 offset:288
	ds_write_b16 v92, v135 offset:432
	v_pk_add_f32 v[46:47], v[46:47], v[58:59]
	v_pk_mul_f32 v[160:161], v[152:153], v[156:157] op_sel_hi:[1,0]
	v_cvt_pk_bf16_f32 v162, v160, v161
	v_pk_fma_f32 v[26:27], v[152:153], v[158:159], v[26:27] op_sel_hi:[1,0,1]
	v_lshlrev_b32_e32 v164, 16, v162
	v_and_b32_e32 v165, 0xffff0000, v162
	v_lshrrev_b32_e32 v163, 16, v162
	ds_write_b16 v92, v162 offset:576
	ds_write_b16 v92, v163 offset:720
	v_pk_add_f32 v[42:43], v[42:43], v[164:165]
	v_pk_mul_f32 v[166:167], v[154:155], v[156:157] op_sel_hi:[1,0]
	v_cvt_pk_bf16_f32 v134, v166, v167
	v_pk_fma_f32 v[28:29], v[154:155], v[158:159], v[28:29] op_sel_hi:[1,0,1]
	v_lshlrev_b32_e32 v58, 16, v134
	v_and_b32_e32 v59, 0xffff0000, v134
	v_lshrrev_b32_e32 v135, 16, v134
	ds_write_b16 v92, v134 offset:864
	ds_write_b16 v92, v135 offset:1008
	v_pk_add_f32 v[40:41], v[40:41], v[58:59]
	s_waitcnt lgkmcnt(0)
	s_barrier
	ds_read_b128 v[88:91], v93
	s_waitcnt lgkmcnt(0)
	global_store_dwordx4 v[44:45], v[88:91], off offset:1792
	s_barrier
	v_add_u32_e32 v16, s44, v32
	v_ashrrev_i32_e32 v17, 31, v16
	v_lshlrev_b64 v[16:17], 11, v[16:17]
	v_lshl_add_u64 v[16:17], s[24:25], 0, v[16:17]
	v_lshlrev_b32_e32 v18, 1, v34
	v_mov_b32_e32 v19, v1
	s_waitcnt vmcnt(1)
	v_pk_mul_f32 v[20:21], v[56:57], v[12:13] op_sel_hi:[0,1]
	v_lshl_add_u64 v[16:17], v[16:17], 0, v[18:19]
	v_cvt_pk_bf16_f32 v19, v20, v21
	v_lshrrev_b32_e32 v20, 16, v19
	ds_write_b16 v35, v20 offset:144
	v_and_b32_e32 v21, 0xffff0000, v19
	v_lshlrev_b32_e32 v20, 16, v19
	v_pk_add_f32 v[22:23], v[50:51], v[20:21]
	v_pk_mul_f32 v[20:21], v[56:57], v[14:15] op_sel_hi:[0,1]
	v_cvt_pk_bf16_f32 v20, v20, v21
	v_lshrrev_b32_e32 v21, 16, v20
	ds_write_b16 v35, v20 offset:288
	ds_write_b16 v35, v21 offset:432
	v_and_b32_e32 v21, 0xffff0000, v20
	v_lshlrev_b32_e32 v20, 16, v20
	v_pk_mul_f32 v[38:39], v[56:57], v[8:9] op_sel_hi:[0,1]
	v_pk_add_f32 v[36:37], v[46:47], v[20:21]
	v_cvt_pk_bf16_f32 v21, v38, v39
	v_and_b32_e32 v39, 0xffff0000, v21
	v_lshlrev_b32_e32 v38, 16, v21
	v_pk_add_f32 v[38:39], v[42:43], v[38:39]
	v_pk_mul_f32 v[42:43], v[56:57], v[10:11] op_sel_hi:[0,1]
	s_movk_i32 s7, 0x104
	v_cvt_pk_bf16_f32 v42, v42, v43
	v_mul_lo_u32 v18, v32, s7
	ds_write_b16 v35, v21 offset:576
	v_lshrrev_b32_e32 v32, 16, v21
	v_lshrrev_b32_e32 v21, 16, v42
	ds_write_b16 v35, v19
	ds_write_b16 v35, v32 offset:720
	ds_write_b16 v35, v42 offset:864
	ds_write_b16 v35, v21 offset:1008
	s_waitcnt lgkmcnt(0)
	s_barrier
	ds_read_b128 v[32:35], v33
	v_add3_u32 v0, 0, v18, v0
	v_add_u32_e32 v18, 0x2400, v0
	v_and_b32_e32 v43, 0xffff0000, v42
	v_lshlrev_b32_e32 v42, 16, v42
	s_waitcnt lgkmcnt(0)
	global_store_dwordx4 v[16:17], v[32:35], off offset:1920
	v_add_u32_e32 v19, 0x2408, v0
	v_add_u32_e32 v20, 0x2410, v0
	v_add_u32_e32 v21, 0x2418, v0
	v_pk_add_f32 v[40:41], v[40:41], v[42:43]
	s_waitcnt lgkmcnt(0)
	s_barrier
	ds_write2_b32 v18, v22, v23 offset1:1
	ds_write2_b32 v19, v36, v37 offset1:1
	ds_write2_b32 v20, v38, v39 offset1:1
	ds_write2_b32 v21, v40, v41 offset1:1
	s_waitcnt lgkmcnt(0)
	s_barrier
	v_add_u32_e32 v16, s44, v31
	v_cmp_gt_i32_e64 s[40:41], 64, v31
	v_lshl_add_u32 v0, v31, 2, 0
	v_ashrrev_i32_e32 v17, 31, v16
	s_and_saveexec_b64 s[20:21], s[40:41]
	s_cbranch_execz .LBB0_830
; #define LBAR() do { asm volatile("s_waitcnt lgkmcnt(0)" ::: "memory"); __builtin_amdgcn_s_barrier(); asm volatile("" ::: "memory"); } while (0)
; __device__ void conv_unit(LAS unsigned char* lds, const float* src, int ld, int sn0, int nvalid, int k0, int krows,
;                           bf16_t* dst, int dn0, int Kdst, int kd0, const float* gs, const float* bs, float* c1, float* c2) {
;     ...
;     if (c1) {
; #pragma unroll
;         for (int j = 0; j < 8; ++j) red[kl * 65 + ng + j] = a1[j];
;         LBAR();
;         if (tid < 64) { float sm = 0.f; for (int q = 0; q < 64; ++q) sm += red[q * 65 + tid]; c1[dn0 + tid] = sm; }
;         LBAR();
	v_add_u32_e32 v31, 0x2400, v0
	ds_read2_b32 v[22:23], v31 offset1:65
	v_add_u32_e32 v36, 0x2800, v0
	ds_read2_b32 v[32:33], v31 offset0:130 offset1:195
	ds_read2_b32 v[34:35], v36 offset0:4 offset1:69
	ds_read2_b32 v[36:37], v36 offset0:134 offset1:199
	s_waitcnt lgkmcnt(3)
	v_add_f32_e32 v22, 0, v22
	v_add_f32_e32 v22, v22, v23
	s_waitcnt lgkmcnt(2)
	v_add_f32_e32 v22, v22, v32
	v_add_u32_e32 v32, 0x2c00, v0
	v_add_f32_e32 v31, v22, v33
	ds_read2_b32 v[22:23], v32 offset0:8 offset1:73
	s_waitcnt lgkmcnt(2)
	v_add_f32_e32 v31, v31, v34
	v_add_f32_e32 v31, v31, v35
	s_waitcnt lgkmcnt(1)
	v_add_f32_e32 v31, v31, v36
	v_add_f32_e32 v31, v31, v37
	ds_read2_b32 v[32:33], v32 offset0:138 offset1:203
	s_waitcnt lgkmcnt(1)
	v_add_f32_e32 v22, v31, v22
	v_add_u32_e32 v31, 0x3000, v0
	ds_read2_b32 v[34:35], v31 offset0:12 offset1:77
	v_add_f32_e32 v36, v22, v23
	ds_read2_b32 v[22:23], v31 offset0:142 offset1:207
	s_waitcnt lgkmcnt(2)
	v_add_f32_e32 v31, v36, v32
	v_add_f32_e32 v31, v31, v33
	s_waitcnt lgkmcnt(1)
	v_add_f32_e32 v31, v31, v34
	v_add_f32_e32 v31, v31, v35
	s_waitcnt lgkmcnt(0)
	v_add_f32_e32 v22, v31, v22
	v_add_u32_e32 v31, 0x3400, v0
	ds_read2_b32 v[32:33], v31 offset0:16 offset1:81
	v_add_f32_e32 v36, v22, v23
	ds_read2_b32 v[22:23], v31 offset0:146 offset1:211
	v_add_u32_e32 v31, 0x3800, v0
	ds_read2_b32 v[34:35], v31 offset0:20 offset1:85
	s_waitcnt lgkmcnt(2)
	v_add_f32_e32 v32, v36, v32
	v_add_f32_e32 v32, v32, v33
	s_waitcnt lgkmcnt(1)
	v_add_f32_e32 v22, v32, v22
	v_add_f32_e32 v22, v22, v23
	s_waitcnt lgkmcnt(0)
	v_add_f32_e32 v34, v22, v34
	ds_read2_b32 v[22:23], v31 offset0:150 offset1:215
	v_add_u32_e32 v31, 0x3c00, v0
	ds_read2_b32 v[32:33], v31 offset0:24 offset1:89
	v_add_f32_e32 v36, v34, v35
	ds_read2_b32 v[34:35], v31 offset0:154 offset1:219
	s_waitcnt lgkmcnt(2)
	v_add_f32_e32 v22, v36, v22
	v_add_f32_e32 v22, v22, v23
	s_waitcnt lgkmcnt(1)
	v_add_f32_e32 v22, v22, v32
	v_add_f32_e32 v22, v22, v33
	v_add_u32_e32 v32, 0x4000, v0
	s_waitcnt lgkmcnt(0)
	v_add_f32_e32 v31, v22, v34
	ds_read2_b32 v[22:23], v32 offset0:28 offset1:93
	ds_read2_b32 v[32:33], v32 offset0:158 offset1:223
	v_add_u32_e32 v36, 0x4400, v0
	v_add_f32_e32 v31, v31, v35
	ds_read2_b32 v[34:35], v36 offset0:32 offset1:97
	s_waitcnt lgkmcnt(2)
	v_add_f32_e32 v22, v31, v22
	v_add_f32_e32 v22, v22, v23
	s_waitcnt lgkmcnt(1)
	v_add_f32_e32 v22, v22, v32
	v_add_f32_e32 v22, v22, v33
	s_waitcnt lgkmcnt(0)
	v_add_f32_e32 v31, v22, v34
	ds_read2_b32 v[22:23], v36 offset0:162 offset1:227
	v_add_u32_e32 v34, 0x4800, v0
	ds_read2_b32 v[32:33], v34 offset0:36 offset1:101
	v_add_f32_e32 v31, v31, v35
	ds_read2_b32 v[34:35], v34 offset0:166 offset1:231
	s_waitcnt lgkmcnt(2)
	v_add_f32_e32 v22, v31, v22
	v_add_f32_e32 v22, v22, v23
	s_waitcnt lgkmcnt(1)
	v_add_f32_e32 v22, v22, v32
	v_add_f32_e32 v22, v22, v33
	v_add_u32_e32 v32, 0x4c00, v0
	s_waitcnt lgkmcnt(0)
	v_add_f32_e32 v31, v22, v34
	ds_read2_b32 v[22:23], v32 offset0:40 offset1:105
	ds_read2_b32 v[32:33], v32 offset0:170 offset1:235
	v_add_u32_e32 v36, 0x5000, v0
	v_add_f32_e32 v31, v31, v35
	ds_read2_b32 v[34:35], v36 offset0:44 offset1:109
	s_waitcnt lgkmcnt(2)
	v_add_f32_e32 v22, v31, v22
	v_add_f32_e32 v22, v22, v23
	s_waitcnt lgkmcnt(1)
	v_add_f32_e32 v22, v22, v32
	v_add_f32_e32 v22, v22, v33
	s_waitcnt lgkmcnt(0)
	v_add_f32_e32 v31, v22, v34
	ds_read2_b32 v[22:23], v36 offset0:174 offset1:239
	v_add_u32_e32 v34, 0x5400, v0
	ds_read2_b32 v[32:33], v34 offset0:48 offset1:113
	v_add_f32_e32 v31, v31, v35
	ds_read2_b32 v[34:35], v34 offset0:178 offset1:243
	s_waitcnt lgkmcnt(2)
	v_add_f32_e32 v22, v31, v22
	v_add_f32_e32 v22, v22, v23
	s_waitcnt lgkmcnt(1)
	v_add_f32_e32 v22, v22, v32
	v_add_f32_e32 v22, v22, v33
	v_add_u32_e32 v32, 0x5800, v0
	s_waitcnt lgkmcnt(0)
	v_add_f32_e32 v31, v22, v34
	ds_read2_b32 v[22:23], v32 offset0:52 offset1:117
	ds_read2_b32 v[32:33], v32 offset0:182 offset1:247
	v_add_u32_e32 v36, 0x5c00, v0
	v_add_f32_e32 v31, v31, v35
	ds_read2_b32 v[34:35], v36 offset0:56 offset1:121
	s_waitcnt lgkmcnt(2)
	v_add_f32_e32 v22, v31, v22
	v_add_f32_e32 v22, v22, v23
	s_waitcnt lgkmcnt(1)
	v_add_f32_e32 v22, v22, v32
	v_add_f32_e32 v22, v22, v33
	s_waitcnt lgkmcnt(0)
	v_add_f32_e32 v31, v22, v34
	ds_read2_b32 v[22:23], v36 offset0:186 offset1:251
	v_add_u32_e32 v34, 0x6000, v0
	ds_read2_b32 v[32:33], v34 offset0:60 offset1:125
	v_add_f32_e32 v31, v31, v35
	ds_read2_b32 v[34:35], v34 offset0:190 offset1:255
	s_waitcnt lgkmcnt(2)
	v_add_f32_e32 v22, v31, v22
	v_add_f32_e32 v22, v22, v23
	s_waitcnt lgkmcnt(1)
	v_add_f32_e32 v22, v22, v32
	v_add_f32_e32 v22, v22, v33
	s_waitcnt lgkmcnt(0)
	v_add_f32_e32 v22, v22, v34
	v_add_f32_e32 v31, v22, v35
	v_lshl_add_u64 v[22:23], v[16:17], 2, s[22:23]
	v_add_co_u32_e32 v22, vcc, 0xee94000, v22
	s_nop 1
	v_addc_co_u32_e32 v23, vcc, 0, v23, vcc
	global_store_dword v[22:23], v31, off

; #define LAS __attribute__((address_space(3)))
; __device__ __forceinline__ int tidx() { int t = threadIdx.x; asm volatile("" : "+v"(t)); return t; }
; __device__ __forceinline__ int prow0(int pm) { return (pm >> 4) * LP + PADR + (pm & 15) * 256; }
; __device__ __forceinline__ int trow(int i) { return (i >> 4) * LP + 4144 + (i & 15); }
; __device__ __forceinline__ void prep_rowstats(const float* stat, int pm, int par, LAS unsigned char* lds) {
;     const int t = tidx();
;     if (t < (pm < 64 ? 256 : 64)) {
;         const int row = pm < 64 ? prow0(pm) + t : trow(t); const f32x4* sp = (const f32x4*)(stat + (size_t)row * 32);
;         float s1 = 0.f, s2 = 0.f;
; #pragma unroll
;         for (int q = 0; q < 8; ++q) { const f32x4 v = sp[q]; s1 += v[0] + v[2]; s2 += v[1] + v[3]; }
;         const float mu = s1 * (1.0f / 1024.0f); const float var = fmaxf(s2 * (1.0f / 1024.0f) - mu * mu, 0.f);
;         ((LAS f32x2*)(lds + RS_OFF + par * 2048))[t] = (f32x2){mu, __builtin_amdgcn_rsqf(var + LN_EPS)};
;     }
; }
.LBB0_832:
	v_readlane_b32 s6, v255, 27
	s_nop 1
	s_cmp_eq_u32 s6, 2
	s_cbranch_scc1 .Lk2_conv_done
	s_add_u32 s18, s86, 0xee8d800
	s_addc_u32 s19, s87, 0
	s_add_u32 s20, s86, 0xee90c00
	s_addc_u32 s21, s87, 0
	v_readlane_b32 s6, v255, 25
	s_cmp_lt_i32 s6, 1
	s_cselect_b64 s[42:43], -1, 0
	s_cmp_gt_i32 s6, 0
	s_cselect_b64 s[12:13], -1, 0
	v_readlane_b32 s14, v253, 41
	v_readlane_b32 s7, v255, 26
	s_add_u32 s6, s84, 0x2080000
	s_waitcnt vmcnt(16)
	v_mov_b32_e32 v16, v198
	v_readlane_b32 s15, v253, 42
	v_cndmask_b32_e64 v0, 0, 1, s[12:13]
	s_addc_u32 s7, s85, 0
	s_andn2_b64 vcc, exec, s[14:15]
	v_readfirstlane_b32 s58, v16
	v_cmp_ne_u32_e64 s[40:41], 1, v0
	s_cbranch_vccnz .LBB0_881
	s_and_b64 vcc, exec, s[40:41]
	s_cbranch_vccnz .LBB0_837
	v_mov_b32_e32 v0, v198
	s_nop 0
	v_cmp_gt_i32_e32 vcc, s1, v0
	s_and_saveexec_b64 s[22:23], vcc
	s_cbranch_execz .LBB0_836
	v_readlane_b32 s14, v253, 47
	v_readlane_b32 s15, v253, 48
	s_nop 0
	v_add_u32_e32 v2, s14, v0
	v_ashrrev_i32_e32 v3, 31, v2
	v_lshlrev_b64 v[2:3], 7, v[2:3]
	v_lshl_add_u64 v[2:3], s[34:35], 0, v[2:3]
	global_load_dwordx4 v[8:11], v[2:3], off
	global_load_dwordx4 v[12:15], v[2:3], off offset:16
	global_load_dwordx4 v[18:21], v[2:3], off offset:32
	global_load_dwordx4 v[22:25], v[2:3], off offset:48
	global_load_dwordx4 v[26:29], v[2:3], off offset:64
	global_load_dwordx4 v[30:33], v[2:3], off offset:80
	global_load_dwordx4 v[34:37], v[2:3], off offset:96
	global_load_dwordx4 v[38:41], v[2:3], off offset:112
	v_lshl_add_u32 v0, v0, 3, 0
	v_add_u32_e32 v0, 0x20000, v0
	s_waitcnt vmcnt(7)
	v_pk_add_f32 v[2:3], v[8:9], v[10:11]
	s_waitcnt vmcnt(6)
	v_pk_add_f32 v[8:9], v[12:13], v[14:15]
	v_pk_add_f32 v[2:3], v[2:3], 0 op_sel_hi:[1,0]
	s_waitcnt vmcnt(5)
	v_pk_add_f32 v[10:11], v[18:19], v[20:21]
	v_pk_add_f32 v[2:3], v[2:3], v[8:9]
	s_waitcnt vmcnt(4)
	v_pk_add_f32 v[12:13], v[22:23], v[24:25]
	v_pk_add_f32 v[2:3], v[2:3], v[10:11]
	s_waitcnt vmcnt(3)
	v_pk_add_f32 v[14:15], v[26:27], v[28:29]
	v_pk_add_f32 v[2:3], v[2:3], v[12:13]
	s_waitcnt vmcnt(2)
	v_pk_add_f32 v[18:19], v[30:31], v[32:33]
	v_pk_add_f32 v[2:3], v[2:3], v[14:15]
	s_waitcnt vmcnt(1)
	v_pk_add_f32 v[20:21], v[34:35], v[36:37]
	v_pk_add_f32 v[2:3], v[2:3], v[18:19]
	s_waitcnt vmcnt(0)
	v_pk_add_f32 v[8:9], v[38:39], v[40:41]
	v_pk_add_f32 v[2:3], v[2:3], v[20:21]
	s_nop 0
	v_pk_add_f32 v[2:3], v[2:3], v[8:9]
	s_nop 0
	v_pk_mul_f32 v[2:3], v[2:3], s[0:1] op_sel_hi:[1,0]
	s_nop 0
	v_fma_f32 v3, -v2, v2, v3
	v_max_f32_e32 v3, 0, v3
	v_add_f32_e32 v3, 0x3727c5ac, v3
	v_rsq_f32_e32 v3, v3
	ds_write_b64 v0, v[2:3]

; __device__ __forceinline__ void run_phase(LAS unsigned char* lds, KP& P_, int ph) {
;     ...
;         if (!tail_first) {
;             gemm_tail(lds, xb, (const bf16_t*)(ob + OUT_WIN), 1024, NPROJ, E, hrank, hsize);
;             dt_units(lds, xb, (const bf16_t*)(ob + OUT_WIN), statB, (const float*)(ws + WS_C1IN), (const float*)(ws + WS_C2IN), (float*)(ws + WS_DT), l > 0 ? 1 : 0, (bf16_t*)(ws + WS_PROJ), hrank, hsize, 2 * hsize); }
;         else if (2 * hsize + hrank < NCHT)
;             dt_units(lds, xb, (const bf16_t*)(ob + OUT_WIN), statB, (const float*)(ws + WS_C1IN), (const float*)(ws + WS_C2IN), (float*)(ws + WS_DT), l > 0 ? 1 : 0, (bf16_t*)(ws + WS_PROJ), 2 * hsize + hrank, NCHT, NCHT);
.LBB0_881:
	v_readlane_b32 s22, v253, 16
	s_add_u32 s12, s86, 0xe9fb800
	v_readlane_b32 s23, v253, 17
	s_addc_u32 s13, s87, 0
	s_mov_b64 s[14:15], -1
	s_and_b64 vcc, exec, s[22:23]
	s_branch .LBB0_896

; #define LAS __attribute__((address_space(3)))
; __device__ __forceinline__ int tidx() { int t = threadIdx.x; asm volatile("" : "+v"(t)); return t; }
; __device__ __forceinline__ void dt_units(LAS unsigned char* lds, const bf16_t* xb, const bf16_t* WinT, const float* stat, const float* c1, const float* c2, float* dtbuf, int fold, bf16_t* proj, const int ufirst, const int ustride, const int uend) {
;     const int tid = tidx(), wid = tid >> 6, lane = tid & 63, fr = lane & 15, fq = lane >> 4, rb4 = wid & 3, kh = wid >> 2;
;     LAS float* red = (LAS float*)lds;
;     for (int u = ufirst; u < uend; u += ustride) {
;         if (u % NCHB == 0) {
;             for (int i = tid; i < PADR * (NPROJ / 8); i += NTHR) { const int r = i / (NPROJ / 8), c8 = (i - r * (NPROJ / 8)) * 8; *(u32x4*)(proj + ((size_t)u * 64 + r) * NPROJ + c8) = (u32x4){0u, 0u, 0u, 0u}; }
;         }
;         const bf16_t* ap = xb + (size_t)(u * 64 + rb4 * 16 + fr) * 1024 + kh * 512 + fq * 8;
;         const bf16_t* bp = WinT + (size_t)(NPROJ + fr) * 1024 + kh * 512 + fq * 8;
;         f32x4 acc = (f32x4){0.f, 0.f, 0.f, 0.f};
; __device__ __forceinline__ void run_phase(LAS unsigned char* lds, KP& P_, int ph) {
;     ...
;             dt_units(lds, xb, (const bf16_t*)(ob + OUT_WIN), statB, (const float*)(ws + WS_C1IN), (const float*)(ws + WS_C2IN), (float*)(ws + WS_DT), l > 0 ? 1 : 0, (bf16_t*)(ws + WS_PROJ), hrank, hsize, 2 * hsize); }
.LBB0_915:
	s_movk_i32 s46, 0x104
	v_readlane_b32 s14, v253, 45
	s_waitcnt vmcnt(0)
	v_mov_b32_e32 v22, v198
	s_cmp_ge_i32 s14, s46
	s_cbranch_scc1 .LBB0_928
	v_ashrrev_i32_e32 v14, 8, v22
	v_and_b32_e32 v10, 15, v22
	v_lshrrev_b32_e32 v0, 2, v22
	v_lshlrev_b32_e32 v2, 9, v14
	v_and_or_b32 v23, v0, 48, v10
	v_ashrrev_i32_e32 v3, 31, v2
	v_lshlrev_b32_e32 v10, 11, v10
	v_mov_b32_e32 v11, v1
	v_lshlrev_b64 v[8:9], 1, v[2:3]
	v_lshl_add_u64 v[10:11], s[6:7], 0, v[10:11]
	v_lshl_add_u64 v[2:3], s[36:37], 0, v[8:9]
	v_and_b32_e32 v0, 48, v22
	v_lshl_add_u64 v[8:9], v[10:11], 0, v[8:9]
	v_lshl_add_u64 v[8:9], v[8:9], 0, v[0:1]
	s_mov_b64 s[6:7], 0x600000
	v_lshl_add_u64 v[12:13], v[8:9], 0, s[6:7]
	v_lshl_or_b32 v8, v14, 6, v23
	s_movk_i32 s7, 0x50
	v_mul_lo_u32 v8, v8, s7
	v_add_u32_e32 v10, 0, v8
	v_ashrrev_i32_e32 v24, 1, v22
	v_lshlrev_b32_e32 v8, 4, v22
	v_mul_lo_u32 v9, v24, s7
	v_and_b32_e32 v8, 16, v8
	s_movk_i32 s6, 0x80
	v_add3_u32 v25, 0, v9, v8
	v_mov_b32_e32 v9, v1
	v_cmp_gt_i32_e64 s[42:43], s6, v22
	v_lshl_add_u64 v[8:9], s[86:87], 0, v[8:9]
	s_mov_b64 s[6:7], 0xee90800
	s_movk_i32 s14, 0x47ff
	v_lshl_add_u64 v[14:15], v[8:9], 0, s[6:7]
	s_mov_b64 s[6:7], 0xee93c00
	v_cmp_lt_i32_e32 vcc, s14, v22
	v_lshl_add_u64 v[16:17], v[8:9], 0, s[6:7]
	v_and_b32_e32 v8, 1, v22
	v_readlane_b32 s14, v253, 45
	v_lshl_add_u64 v[2:3], v[2:3], 0, v[0:1]
	v_cmp_eq_u32_e64 s[44:45], 1, v8
	s_xor_b64 s[6:7], vcc, -1
	v_add_u32_e32 v26, v10, v0
	s_mov_b32 s18, s14
	s_branch .LBB0_918
